# hand-written SWA compute (plain softmax over 5 aligned key blocks per 32-query sub-block) on top of MLA rewrite, de-serialized swa/sgu staging loads
# speedup vs baseline: 1.0266x; 1.0014x over previous
; #define LAS __attribute__((address_space(3)))
; __device__ __forceinline__ f32x16 mfma32(bf16x8 a, bf16x8 b, f32x16 c) { return __builtin_amdgcn_mfma_f32_32x32x16_bf16(a, b, c, 0, 0, 0); }
; template <int NQK, int NDV, int KSTR, int VSTR> ...
;     ...
;   const LAS unsigned char* ka = Kt + c * KSTR + h * 16;
;   bf16x8 kc0 = *(const LAS bf16x8*)(ka), kc1 = *(const LAS bf16x8*)(ka + 32 * KSTR);
; #pragma unroll
;   for (int st = 0; st < NQK; ++st) {
;     bf16x8 kn0 = kc0, kn1 = kc1;
;     if (st + 1 < NQK) { kn0 = *(const LAS bf16x8*)(ka + (st + 1) * 32); kn1 = *(const LAS bf16x8*)(ka + 32 * KSTR + (st + 1) * 32); }
;     s0 = mfma32(kc0, qf[st], s0);
;     s1 = mfma32(kc1, qf[st], s1);
;     if (st + 1 < NQK) __builtin_amdgcn_sched_group_barrier(0x100, 2, 0);
;     __builtin_amdgcn_sched_group_barrier(0x008, 2, 0);
;     kc0 = kn0; kc1 = kn1;
;   }
;     ...
;   for (int it = bid_; it < 512; it += grd_) {
;     const int b = it >> 7, r = it & 127, kvh = r >> 6, qblk = r & 63, t0 = qblk * 64, hq = kvh * 8 + wid;
;     const size_t tokb = (size_t)b * SEQ;
;     bf16x8 qf[2][4];
;     bf16_t* qrow0 = h + (tokb + t0 + c) * LDH + C_QA + hq * 64;
; #pragma unroll
;     for (int sub = 0; sub < 2; ++sub)
; #pragma unroll
;       for (int st = 0; st < 4; ++st) qf[sub][st] = *(const bf16x8*)(qrow0 + (size_t)sub * 32 * LDH + 16 * st + 8 * hh);
;     { const int key = tid >> 3, ch = tid & 7;
; #pragma unroll
;       for (int j = 0; j < 3; ++j) { int kp = t0 - 128 + 64 * j + key; kp = kp < 0 ? 0 : kp;
;         const bf16_t* src = h + (tokb + kp) * LDH + C_KA + kvh * 64 + ch * 8;
;         *(LAS u32x4*)(lds + j * 2 * TB + key * STR + ch * 16) = *(const u32x4*)src;
;         *(LAS u32x4*)(lds + j * 2 * TB + TB + key * VST + ch * 16) = *(const u32x4*)(src + (C_VA - C_KA)); } }
;     __syncthreads();
;     const float sink2 = p->sinks[l * 16 + hq] * LOG2E;
.LBB0_585:
	s_ashr_i32 s6, s16, 7
	s_and_b32 s23, s20, 0xfc0
	s_ashr_i32 s7, s6, 31
	s_bfe_u32 s1, s16, 0x10006
	s_lshl_b64 s[6:7], s[6:7], 12
	v_or_b32_e32 v151, s23, v133
	s_lshl_b32 s0, s1, 3
	v_or_b32_e32 v0, s6, v151
	s_add_i32 s0, s0, s19
	v_mad_u64_u32 v[0:1], s[8:9], v0, s91, v[130:131]
	v_mov_b32_e32 v2, 0x2280
	s_lshl_b32 s8, s0, 6
	v_mad_i32_i24 v1, s7, v2, v1
	s_ashr_i32 s9, s8, 31
	v_lshl_add_u64 v[136:137], s[8:9], 1, v[0:1]
	v_lshl_add_u64 v[0:1], v[136:137], 0, v[96:97]
	global_load_dwordx4 v[126:129], v[0:1], off
	global_load_dwordx4 v[122:125], v[0:1], off offset:32
	global_load_dwordx4 v[118:121], v[0:1], off offset:64
	global_load_dwordx4 v[114:117], v[0:1], off offset:96
	v_add_co_u32_e32 v0, vcc, s68, v0
	v_add_u32_e32 v6, s23, v139
	s_nop 0
	v_addc_co_u32_e32 v1, vcc, 0, v1, vcc
	global_load_dwordx4 v[110:113], v[0:1], off
	global_load_dwordx4 v[106:109], v[0:1], off offset:32
	global_load_dwordx4 v[102:105], v[0:1], off offset:64
	global_load_dwordx4 v[98:101], v[0:1], off offset:96
	v_max_i32_e32 v0, 0, v6
	v_mov_b32_e32 v1, v97
	v_lshl_add_u64 v[0:1], s[6:7], 0, v[0:1]
	v_mad_u64_u32 v[2:3], s[8:9], v0, s91, v[130:131]
	v_mad_i32_i24 v3, v1, s91, v3
	s_lshl_b32 s92, s1, 7
	v_lshl_add_u64 v[0:1], v[2:3], 0, s[92:93]
	v_mov_b32_e32 v135, v97
	v_lshl_add_u64 v[4:5], v[0:1], 0, v[134:135]
	global_load_dwordx4 v[8:11], v[4:5], off offset:2048
	global_load_dwordx4 v[12:15], v[4:5], off offset:2304
	s_add_i32 s0, s0, s18
	s_ashr_i32 s1, s0, 31
	s_lshl_b64 s[0:1], s[0:1], 2
	s_waitcnt lgkmcnt(0)
	s_add_u32 s0, s12, s0
	s_addc_u32 s1, s13, s1
	v_add_u32_e32 v172, 0xffffff80, v151
	v_max_i32_e32 v0, 0xffffffc0, v6
	v_add_u32_e32 v0, 64, v0
	v_mov_b32_e32 v1, v97
	v_lshl_add_u64 v[0:1], s[6:7], 0, v[0:1]
	v_mad_u64_u32 v[2:3], s[8:9], v0, s91, v[130:131]
	v_mad_i32_i24 v3, v1, s91, v3
	v_lshl_add_u64 v[0:1], v[2:3], 0, s[92:93]
	v_lshl_add_u64 v[4:5], v[0:1], 0, v[134:135]
	global_load_dwordx4 v[16:19], v[4:5], off offset:2048
	global_load_dwordx4 v[20:23], v[4:5], off offset:2304
	v_add_u32_e32 v0, s23, v138
	v_max_i32_e32 v0, 0, v0
	v_mov_b32_e32 v1, v97
	v_lshl_add_u64 v[0:1], s[6:7], 0, v[0:1]
	v_mad_u64_u32 v[2:3], s[6:7], v0, s91, v[130:131]
	v_mad_i32_i24 v3, v1, s91, v3
	v_lshl_add_u64 v[0:1], v[2:3], 0, s[92:93]
	v_lshl_add_u64 v[4:5], v[0:1], 0, v[134:135]
	global_load_dwordx4 v[24:27], v[4:5], off offset:2048
	global_load_dwordx4 v[28:31], v[4:5], off offset:2304
	global_load_dword v32, v97, s[0:1]
	v_add_u32_e32 v7, v142, v140
	s_waitcnt vmcnt(6)
	ds_write_b128 v7, v[8:11]
	v_add_u32_e32 v4, v143, v140
	s_waitcnt vmcnt(5)
	ds_write_b128 v4, v[12:15] offset:12288
	v_add_u32_e32 v6, v144, v140
	s_waitcnt vmcnt(4)
	ds_write_b128 v6, v[16:19] offset:24576
	v_add_u32_e32 v4, v145, v140
	s_waitcnt vmcnt(3)
	ds_write_b128 v4, v[20:23] offset:36864
	v_add_u32_e32 v6, v146, v140
	s_waitcnt vmcnt(2)
	ds_write_b128 v6, v[24:27] offset:49152
	s_waitcnt vmcnt(1)
	ds_write_b128 v149, v[28:31] offset:61440
	s_waitcnt lgkmcnt(0)
	s_barrier
	s_add_i32 s1, s23, 0xffffff81
	s_waitcnt vmcnt(0)
	v_mul_f32_e32 v135, 0x3fb8aa3b, v32
	s_mov_b32 s69, 0
	ds_read_b128 v[80:83], v150 offset:0
	ds_read_b128 v[84:87], v150 offset:32
	ds_read_b128 v[88:91], v150 offset:64
	ds_read_b128 v[92:95], v150 offset:96
	s_waitcnt lgkmcnt(3)
	v_mfma_f32_32x32x16_bf16 v[0:15], v[80:83], v[126:129], 0
	ds_read_b128 v[80:83], v150 offset:4608
	s_waitcnt lgkmcnt(3)
	v_mfma_f32_32x32x16_bf16 v[0:15], v[84:87], v[122:125], v[0:15]
	ds_read_b128 v[84:87], v150 offset:4640
	s_waitcnt lgkmcnt(3)
	v_mfma_f32_32x32x16_bf16 v[0:15], v[88:91], v[118:121], v[0:15]
	ds_read_b128 v[88:91], v150 offset:4672
	s_waitcnt lgkmcnt(3)
	v_mfma_f32_32x32x16_bf16 v[0:15], v[92:95], v[114:117], v[0:15]
	ds_read_b128 v[92:95], v150 offset:4704
	s_waitcnt lgkmcnt(3)
	v_mfma_f32_32x32x16_bf16 v[16:31], v[80:83], v[126:129], 0
	ds_read_b128 v[80:83], v150 offset:24576
	s_waitcnt lgkmcnt(3)
	v_mfma_f32_32x32x16_bf16 v[16:31], v[84:87], v[122:125], v[16:31]
	ds_read_b128 v[84:87], v150 offset:24608
	s_waitcnt lgkmcnt(3)
	v_mfma_f32_32x32x16_bf16 v[16:31], v[88:91], v[118:121], v[16:31]
	ds_read_b128 v[88:91], v150 offset:24640
	s_waitcnt lgkmcnt(3)
	v_mfma_f32_32x32x16_bf16 v[16:31], v[92:95], v[114:117], v[16:31]
	ds_read_b128 v[92:95], v150 offset:24672
	s_waitcnt lgkmcnt(3)
	v_mfma_f32_32x32x16_bf16 v[32:47], v[80:83], v[126:129], 0
	ds_read_b128 v[80:83], v150 offset:29184
	s_waitcnt lgkmcnt(3)
	v_mfma_f32_32x32x16_bf16 v[32:47], v[84:87], v[122:125], v[32:47]
	ds_read_b128 v[84:87], v150 offset:29216
	s_waitcnt lgkmcnt(3)
	v_mfma_f32_32x32x16_bf16 v[32:47], v[88:91], v[118:121], v[32:47]
	ds_read_b128 v[88:91], v150 offset:29248
	s_waitcnt lgkmcnt(3)
	v_mfma_f32_32x32x16_bf16 v[32:47], v[92:95], v[114:117], v[32:47]
	ds_read_b128 v[92:95], v150 offset:29280
	s_waitcnt lgkmcnt(3)
	v_mfma_f32_32x32x16_bf16 v[48:63], v[80:83], v[126:129], 0
	ds_read_b128 v[80:83], v150 offset:49152
	s_waitcnt lgkmcnt(3)
	v_mfma_f32_32x32x16_bf16 v[48:63], v[84:87], v[122:125], v[48:63]
	ds_read_b128 v[84:87], v150 offset:49184
	s_waitcnt lgkmcnt(3)
	v_mfma_f32_32x32x16_bf16 v[48:63], v[88:91], v[118:121], v[48:63]
	ds_read_b128 v[88:91], v150 offset:49216
	s_waitcnt lgkmcnt(3)
	v_mfma_f32_32x32x16_bf16 v[48:63], v[92:95], v[114:117], v[48:63]
	ds_read_b128 v[92:95], v150 offset:49248
	s_waitcnt lgkmcnt(3)
	v_mfma_f32_32x32x16_bf16 v[64:79], v[80:83], v[126:129], 0
	s_waitcnt lgkmcnt(2)
	v_mfma_f32_32x32x16_bf16 v[64:79], v[84:87], v[122:125], v[64:79]
	s_waitcnt lgkmcnt(1)
	v_mfma_f32_32x32x16_bf16 v[64:79], v[88:91], v[118:121], v[64:79]
	s_waitcnt lgkmcnt(0)
; template <int NQK, int NDV, int KSTR, int VSTR> ...
;     ...
;   if (domask) {
; #pragma unroll
;     for (int r = 0; r < 16; ++r) { const int kp = kpos0 + (r & 3) + 8 * (r >> 2) + 4 * h;
;       const bool v0 = (kp <= qpos) && (kp > qpos - window) && (kp >= 0);
;       const bool v1 = (kp + 32 <= qpos) && (kp + 32 > qpos - window) && (kp + 32 >= 0);
;       s0[r] = v0 ? s0[r] : -1e30f; s1[r] = v1 ? s1[r] : -1e30f; }
;   }
;     ...
;       for (int j = 0; j < 3; ++j) { const int k0 = t0 - 128 + 64 * j;
;         if (k0 + 63 >= 0 && k0 + 63 >= t0 + 32 * sub - 127 && k0 <= t0 + 32 * sub + 31)
;           attn_tile<4, 2, STR, VST>(qf[sub], o, m, ls, lds + j * 2 * TB, lds + j * 2 * TB + TB, lane, qpos, k0, 128, true); }
	v_mfma_f32_32x32x16_bf16 v[64:79], v[92:95], v[114:117], v[64:79]
	v_sub_u32_e32 v156, v133, v132
	v_mov_b32_e32 v155, 0xf149f2ca
	s_nop 4
	s_nop 4
	v_cmp_gt_i32_e64 s[26:27], 0, v156
	v_cmp_gt_i32_e64 s[28:29], 1, v156
	v_cmp_gt_i32_e64 s[30:31], 2, v156
	v_cmp_gt_i32_e64 s[34:35], 3, v156
	v_cndmask_b32_e64 v0, v155, v0, s[26:27]
	v_cndmask_b32_e64 v1, v155, v1, s[28:29]
	v_cndmask_b32_e64 v2, v155, v2, s[30:31]
	v_cndmask_b32_e64 v3, v155, v3, s[34:35]
	v_cmp_gt_i32_e64 s[26:27], 8, v156
	v_cmp_gt_i32_e64 s[28:29], 9, v156
	v_cmp_gt_i32_e64 s[30:31], 10, v156
	v_cmp_gt_i32_e64 s[34:35], 11, v156
	v_cndmask_b32_e64 v4, v155, v4, s[26:27]
	v_cndmask_b32_e64 v5, v155, v5, s[28:29]
	v_cndmask_b32_e64 v6, v155, v6, s[30:31]
	v_cndmask_b32_e64 v7, v155, v7, s[34:35]
	v_cmp_gt_i32_e64 s[26:27], 16, v156
	v_cmp_gt_i32_e64 s[28:29], 17, v156
	v_cmp_gt_i32_e64 s[30:31], 18, v156
	v_cmp_gt_i32_e64 s[34:35], 19, v156
	v_cndmask_b32_e64 v8, v155, v8, s[26:27]
	v_cndmask_b32_e64 v9, v155, v9, s[28:29]
	v_cndmask_b32_e64 v10, v155, v10, s[30:31]
	v_cndmask_b32_e64 v11, v155, v11, s[34:35]
	v_cmp_gt_i32_e64 s[26:27], 24, v156
	v_cmp_gt_i32_e64 s[28:29], 25, v156
	v_cmp_gt_i32_e64 s[30:31], 26, v156
	v_cmp_gt_i32_e64 s[34:35], 27, v156
	v_cndmask_b32_e64 v12, v155, v12, s[26:27]
	v_cndmask_b32_e64 v13, v155, v13, s[28:29]
	v_cndmask_b32_e64 v14, v155, v14, s[30:31]
	v_cndmask_b32_e64 v15, v155, v15, s[34:35]
	v_cmp_le_i32_e64 s[26:27], 0, v156
	v_cmp_le_i32_e64 s[28:29], 1, v156
	v_cmp_le_i32_e64 s[30:31], 2, v156
	v_cmp_le_i32_e64 s[34:35], 3, v156
	v_cndmask_b32_e64 v64, v155, v64, s[26:27]
	v_cndmask_b32_e64 v65, v155, v65, s[28:29]
	v_cndmask_b32_e64 v66, v155, v66, s[30:31]
	v_cndmask_b32_e64 v67, v155, v67, s[34:35]
	v_cmp_le_i32_e64 s[26:27], 8, v156
	v_cmp_le_i32_e64 s[28:29], 9, v156
	v_cmp_le_i32_e64 s[30:31], 10, v156
	v_cmp_le_i32_e64 s[34:35], 11, v156
	v_cndmask_b32_e64 v68, v155, v68, s[26:27]
	v_cndmask_b32_e64 v69, v155, v69, s[28:29]
	v_cndmask_b32_e64 v70, v155, v70, s[30:31]
	v_cndmask_b32_e64 v71, v155, v71, s[34:35]
	v_cmp_le_i32_e64 s[26:27], 16, v156
	v_cmp_le_i32_e64 s[28:29], 17, v156
	v_cmp_le_i32_e64 s[30:31], 18, v156
	v_cmp_le_i32_e64 s[34:35], 19, v156
	v_cndmask_b32_e64 v72, v155, v72, s[26:27]
	v_cndmask_b32_e64 v73, v155, v73, s[28:29]
	v_cndmask_b32_e64 v74, v155, v74, s[30:31]
	v_cndmask_b32_e64 v75, v155, v75, s[34:35]
	v_cmp_le_i32_e64 s[26:27], 24, v156
	v_cmp_le_i32_e64 s[28:29], 25, v156
	v_cmp_le_i32_e64 s[30:31], 26, v156
	v_cmp_le_i32_e64 s[34:35], 27, v156
	v_cndmask_b32_e64 v76, v155, v76, s[26:27]
	v_cndmask_b32_e64 v77, v155, v77, s[28:29]
	v_cndmask_b32_e64 v78, v155, v78, s[30:31]
	v_cndmask_b32_e64 v79, v155, v79, s[34:35]
	s_add_u32 s36, s23, 0
	s_cmp_ge_u32 s36, 128
	s_cbranch_scc1 .Lsw0_ok0
	v_mov_b32_e32 v0, v155
	v_mov_b32_e32 v1, v155
	v_mov_b32_e32 v2, v155
	v_mov_b32_e32 v3, v155
	v_mov_b32_e32 v4, v155
	v_mov_b32_e32 v5, v155
	v_mov_b32_e32 v6, v155
	v_mov_b32_e32 v7, v155
	v_mov_b32_e32 v8, v155
	v_mov_b32_e32 v9, v155
	v_mov_b32_e32 v10, v155
	v_mov_b32_e32 v11, v155
	v_mov_b32_e32 v12, v155
	v_mov_b32_e32 v13, v155
	v_mov_b32_e32 v14, v155
	v_mov_b32_e32 v15, v155
.Lsw0_ok0:
	s_add_u32 s36, s23, 32
	s_cmp_ge_u32 s36, 128
	s_cbranch_scc1 .Lsw0_ok1
	v_mov_b32_e32 v16, v155
	v_mov_b32_e32 v17, v155
	v_mov_b32_e32 v18, v155
	v_mov_b32_e32 v19, v155
	v_mov_b32_e32 v20, v155
	v_mov_b32_e32 v21, v155
	v_mov_b32_e32 v22, v155
	v_mov_b32_e32 v23, v155
	v_mov_b32_e32 v24, v155
	v_mov_b32_e32 v25, v155
	v_mov_b32_e32 v26, v155
	v_mov_b32_e32 v27, v155
	v_mov_b32_e32 v28, v155
	v_mov_b32_e32 v29, v155
	v_mov_b32_e32 v30, v155
	v_mov_b32_e32 v31, v155
.Lsw0_ok1:
	s_add_u32 s36, s23, 64
	s_cmp_ge_u32 s36, 128
	s_cbranch_scc1 .Lsw0_ok2
	v_mov_b32_e32 v32, v155
	v_mov_b32_e32 v33, v155
	v_mov_b32_e32 v34, v155
	v_mov_b32_e32 v35, v155
	v_mov_b32_e32 v36, v155
	v_mov_b32_e32 v37, v155
	v_mov_b32_e32 v38, v155
	v_mov_b32_e32 v39, v155
	v_mov_b32_e32 v40, v155
	v_mov_b32_e32 v41, v155
	v_mov_b32_e32 v42, v155
	v_mov_b32_e32 v43, v155
	v_mov_b32_e32 v44, v155
	v_mov_b32_e32 v45, v155
	v_mov_b32_e32 v46, v155
	v_mov_b32_e32 v47, v155
.Lsw0_ok2:
	s_add_u32 s36, s23, 96
	s_cmp_ge_u32 s36, 128
	s_cbranch_scc1 .Lsw0_ok3
	v_mov_b32_e32 v48, v155
	v_mov_b32_e32 v49, v155
	v_mov_b32_e32 v50, v155
	v_mov_b32_e32 v51, v155
	v_mov_b32_e32 v52, v155
	v_mov_b32_e32 v53, v155
	v_mov_b32_e32 v54, v155
	v_mov_b32_e32 v55, v155
	v_mov_b32_e32 v56, v155
	v_mov_b32_e32 v57, v155
	v_mov_b32_e32 v58, v155
	v_mov_b32_e32 v59, v155
	v_mov_b32_e32 v60, v155
	v_mov_b32_e32 v61, v155
	v_mov_b32_e32 v62, v155
	v_mov_b32_e32 v63, v155
; __device__ __forceinline__ float fexp2(float x) { return __builtin_amdgcn_exp2f(x); }
; __device__ __forceinline__ float frcp(float x) { return __builtin_amdgcn_rcpf(x); }
; template <int NQK, int NDV, int KSTR, int VSTR> ...
;     ...
;   float mx = fmaxf(s0[0], s1[0]);
; #pragma unroll
;   for (int r = 1; r < 16; ++r) mx = fmaxf(mx, fmaxf(s0[r], s1[r]));
;   mx = fmaxf(mx, __shfl_xor(mx, 32));
;   if (__builtin_amdgcn_ballot_w64(mx > m + 8.0f) != 0ull) {
;     const float mn = fmaxf(m, mx), alpha = fexp2(m - mn);
;     m = mn; l *= alpha;
; #pragma unroll
;     for (int d = 0; d < NDV; ++d) o[d] *= alpha;
;   }
;   float ps = 0.f;
; #pragma unroll
;   for (int r = 0; r < 16; ++r) { s0[r] = fexp2(s0[r] - m); s1[r] = fexp2(s1[r] - m); ps += s0[r] + s1[r]; }
;   l += ps;
;   bf16x8 pf[4];
; #pragma unroll
;   for (int s = 0; s < 2; ++s) {
;     u32x4 w0, w1;
;     w0.x = pk2(s0[8 * s + 0], s0[8 * s + 1]); w0.y = pk2(s0[8 * s + 2], s0[8 * s + 3]); w0.z = pk2(s0[8 * s + 4], s0[8 * s + 5]); w0.w = pk2(s0[8 * s + 6], s0[8 * s + 7]);
;     w1.x = pk2(s1[8 * s + 0], s1[8 * s + 1]); w1.y = pk2(s1[8 * s + 2], s1[8 * s + 3]); w1.z = pk2(s1[8 * s + 4], s1[8 * s + 5]); w1.w = pk2(s1[8 * s + 6], s1[8 * s + 7]);
;     pf[s] = __builtin_bit_cast(bf16x8, w0); pf[2 + s] = __builtin_bit_cast(bf16x8, w1);
;   }
;     ...
;       const float inv = frcp(ls + __shfl_xor(ls, 32) + fexp2(sink2 - m));
.Lsw0_ok3:
	v_max3_f32 v152, v0, v1, v2
	v_max3_f32 v152, v152, v3, v4
	v_max3_f32 v152, v152, v5, v6
	v_max3_f32 v152, v152, v7, v8
	v_max3_f32 v152, v152, v9, v10
	v_max3_f32 v152, v152, v11, v12
	v_max3_f32 v152, v152, v13, v14
	v_max3_f32 v152, v152, v15, v16
	v_max3_f32 v152, v152, v17, v18
	v_max3_f32 v152, v152, v19, v20
	v_max3_f32 v152, v152, v21, v22
	v_max3_f32 v152, v152, v23, v24
	v_max3_f32 v152, v152, v25, v26
	v_max3_f32 v152, v152, v27, v28
	v_max3_f32 v152, v152, v29, v30
	v_max3_f32 v152, v152, v31, v32
	v_max3_f32 v152, v152, v33, v34
	v_max3_f32 v152, v152, v35, v36
	v_max3_f32 v152, v152, v37, v38
	v_max3_f32 v152, v152, v39, v40
	v_max3_f32 v152, v152, v41, v42
	v_max3_f32 v152, v152, v43, v44
	v_max3_f32 v152, v152, v45, v46
	v_max3_f32 v152, v152, v47, v48
	v_max3_f32 v152, v152, v49, v50
	v_max3_f32 v152, v152, v51, v52
	v_max3_f32 v152, v152, v53, v54
	v_max3_f32 v152, v152, v55, v56
	v_max3_f32 v152, v152, v57, v58
	v_max3_f32 v152, v152, v59, v60
	v_max3_f32 v152, v152, v61, v62
	v_max3_f32 v152, v152, v63, v64
	v_max3_f32 v152, v152, v65, v66
	v_max3_f32 v152, v152, v67, v68
	v_max3_f32 v152, v152, v69, v70
	v_max3_f32 v152, v152, v71, v72
	v_max3_f32 v152, v152, v73, v74
	v_max3_f32 v152, v152, v75, v76
	v_max3_f32 v152, v152, v77, v78
	v_max_f32_e32 v152, v152, v79
	v_mov_b32_e32 v153, v152
	s_nop 1
	v_permlane32_swap_b32_e32 v152, v153
	s_nop 0
	v_max3_f32 v152, v152, v153, v135
	ds_read_b64_tr_b16 v[192:193], v147 offset:12288
	ds_read_b64_tr_b16 v[194:195], v147 offset:13824
	ds_read_b64_tr_b16 v[196:197], v147 offset:12352
	ds_read_b64_tr_b16 v[198:199], v147 offset:13888
	ds_read_b64_tr_b16 v[200:201], v147 offset:15360
	ds_read_b64_tr_b16 v[202:203], v147 offset:16896
	ds_read_b64_tr_b16 v[204:205], v147 offset:15424
	ds_read_b64_tr_b16 v[206:207], v147 offset:16960
	v_mov_b32_e32 v157, 0
	v_mov_b32_e32 v158, 0
	v_sub_f32_e32 v0, v0, v152
	v_sub_f32_e32 v1, v1, v152
	v_exp_f32_e32 v0, v0
	v_exp_f32_e32 v1, v1
	v_sub_f32_e32 v2, v2, v152
	v_sub_f32_e32 v3, v3, v152
	v_exp_f32_e32 v2, v2
	v_exp_f32_e32 v3, v3
	v_add_f32_e32 v157, v157, v0
	v_add_f32_e32 v158, v158, v1
	v_sub_f32_e32 v4, v4, v152
	v_sub_f32_e32 v5, v5, v152
	v_exp_f32_e32 v4, v4
	v_exp_f32_e32 v5, v5
	v_add_f32_e32 v157, v157, v2
	v_add_f32_e32 v158, v158, v3
	v_cvt_pk_bf16_f32 v0, v0, v1
	v_sub_f32_e32 v6, v6, v152
	v_sub_f32_e32 v7, v7, v152
	v_exp_f32_e32 v6, v6
	v_exp_f32_e32 v7, v7
	v_add_f32_e32 v157, v157, v4
	v_add_f32_e32 v158, v158, v5
	v_cvt_pk_bf16_f32 v1, v2, v3
	v_sub_f32_e32 v8, v8, v152
	v_sub_f32_e32 v9, v9, v152
	v_exp_f32_e32 v8, v8
	v_exp_f32_e32 v9, v9
	v_add_f32_e32 v157, v157, v6
	v_add_f32_e32 v158, v158, v7
	v_cvt_pk_bf16_f32 v2, v4, v5
	v_sub_f32_e32 v10, v10, v152
	v_sub_f32_e32 v11, v11, v152
	v_exp_f32_e32 v10, v10
	v_exp_f32_e32 v11, v11
	v_add_f32_e32 v157, v157, v8
	v_add_f32_e32 v158, v158, v9
	v_cvt_pk_bf16_f32 v3, v6, v7
	v_sub_f32_e32 v12, v12, v152
	v_sub_f32_e32 v13, v13, v152
	v_exp_f32_e32 v12, v12
	v_exp_f32_e32 v13, v13
	v_add_f32_e32 v157, v157, v10
	v_add_f32_e32 v158, v158, v11
	v_cvt_pk_bf16_f32 v4, v8, v9
	v_sub_f32_e32 v14, v14, v152
	v_sub_f32_e32 v15, v15, v152
	v_exp_f32_e32 v14, v14
	v_exp_f32_e32 v15, v15
	v_add_f32_e32 v157, v157, v12
	v_add_f32_e32 v158, v158, v13
	v_cvt_pk_bf16_f32 v5, v10, v11
	s_nop 0
	v_add_f32_e32 v157, v157, v14
	v_add_f32_e32 v158, v158, v15
	v_cvt_pk_bf16_f32 v6, v12, v13
	v_cvt_pk_bf16_f32 v7, v14, v15
	v_sub_f32_e32 v16, v16, v152
	v_sub_f32_e32 v17, v17, v152
	v_exp_f32_e32 v16, v16
	v_exp_f32_e32 v17, v17
	v_sub_f32_e32 v18, v18, v152
	v_sub_f32_e32 v19, v19, v152
	v_exp_f32_e32 v18, v18
	v_exp_f32_e32 v19, v19
	v_add_f32_e32 v157, v157, v16
	v_add_f32_e32 v158, v158, v17
	v_sub_f32_e32 v20, v20, v152
	v_sub_f32_e32 v21, v21, v152
	v_exp_f32_e32 v20, v20
	v_exp_f32_e32 v21, v21
	v_add_f32_e32 v157, v157, v18
	v_add_f32_e32 v158, v158, v19
	v_cvt_pk_bf16_f32 v16, v16, v17
	v_sub_f32_e32 v22, v22, v152
	v_sub_f32_e32 v23, v23, v152
	v_exp_f32_e32 v22, v22
	v_exp_f32_e32 v23, v23
	v_add_f32_e32 v157, v157, v20
	v_add_f32_e32 v158, v158, v21
	v_cvt_pk_bf16_f32 v17, v18, v19
	v_sub_f32_e32 v24, v24, v152
	v_sub_f32_e32 v25, v25, v152
	v_exp_f32_e32 v24, v24
	v_exp_f32_e32 v25, v25
	v_add_f32_e32 v157, v157, v22
	v_add_f32_e32 v158, v158, v23
	v_cvt_pk_bf16_f32 v18, v20, v21
	v_sub_f32_e32 v26, v26, v152
	v_sub_f32_e32 v27, v27, v152
	v_exp_f32_e32 v26, v26
	v_exp_f32_e32 v27, v27
	v_add_f32_e32 v157, v157, v24
	v_add_f32_e32 v158, v158, v25
	v_cvt_pk_bf16_f32 v19, v22, v23
	v_sub_f32_e32 v28, v28, v152
	v_sub_f32_e32 v29, v29, v152
	v_exp_f32_e32 v28, v28
	v_exp_f32_e32 v29, v29
	v_add_f32_e32 v157, v157, v26
	v_add_f32_e32 v158, v158, v27
	v_cvt_pk_bf16_f32 v20, v24, v25
	v_sub_f32_e32 v30, v30, v152
	v_sub_f32_e32 v31, v31, v152
	v_exp_f32_e32 v30, v30
	v_exp_f32_e32 v31, v31
	v_add_f32_e32 v157, v157, v28
	v_add_f32_e32 v158, v158, v29
	v_cvt_pk_bf16_f32 v21, v26, v27
	s_nop 0
	v_add_f32_e32 v157, v157, v30
	v_add_f32_e32 v158, v158, v31
	v_cvt_pk_bf16_f32 v22, v28, v29
	v_cvt_pk_bf16_f32 v23, v30, v31
	v_sub_f32_e32 v32, v32, v152
	v_sub_f32_e32 v33, v33, v152
	v_exp_f32_e32 v32, v32
	v_exp_f32_e32 v33, v33
	v_sub_f32_e32 v34, v34, v152
	v_sub_f32_e32 v35, v35, v152
	v_exp_f32_e32 v34, v34
	v_exp_f32_e32 v35, v35
	v_add_f32_e32 v157, v157, v32
	v_add_f32_e32 v158, v158, v33
	v_sub_f32_e32 v36, v36, v152
	v_sub_f32_e32 v37, v37, v152
	v_exp_f32_e32 v36, v36
	v_exp_f32_e32 v37, v37
	v_add_f32_e32 v157, v157, v34
	v_add_f32_e32 v158, v158, v35
	v_cvt_pk_bf16_f32 v32, v32, v33
	v_sub_f32_e32 v38, v38, v152
	v_sub_f32_e32 v39, v39, v152
	v_exp_f32_e32 v38, v38
; #define LAS __attribute__((address_space(3)))
; __device__ __forceinline__ float fexp2(float x) { return __builtin_amdgcn_exp2f(x); }
; __device__ __forceinline__ f32x16 mfma32(bf16x8 a, bf16x8 b, f32x16 c) { return __builtin_amdgcn_mfma_f32_32x32x16_bf16(a, b, c, 0, 0, 0); }
; __device__ __forceinline__ v4i16_t vtr(const LAS unsigned char* p) { return __builtin_amdgcn_ds_read_tr16_b64_v4i16((LAS v4i16_t*)p); }
; template <int NQK, int NDV, int KSTR, int VSTR> ...
;     ...
;   float ps = 0.f;
; #pragma unroll
;   for (int r = 0; r < 16; ++r) { s0[r] = fexp2(s0[r] - m); s1[r] = fexp2(s1[r] - m); ps += s0[r] + s1[r]; }
;   l += ps;
;   bf16x8 pf[4];
; #pragma unroll
;   for (int s = 0; s < 2; ++s) {
;     u32x4 w0, w1;
;     w0.x = pk2(s0[8 * s + 0], s0[8 * s + 1]); w0.y = pk2(s0[8 * s + 2], s0[8 * s + 3]); w0.z = pk2(s0[8 * s + 4], s0[8 * s + 5]); w0.w = pk2(s0[8 * s + 6], s0[8 * s + 7]);
;     w1.x = pk2(s1[8 * s + 0], s1[8 * s + 1]); w1.y = pk2(s1[8 * s + 2], s1[8 * s + 3]); w1.z = pk2(s1[8 * s + 4], s1[8 * s + 5]); w1.w = pk2(s1[8 * s + 6], s1[8 * s + 7]);
;     pf[s] = __builtin_bit_cast(bf16x8, w0); pf[2 + s] = __builtin_bit_cast(bf16x8, w1);
;   }
;   const int i16 = lane & 15, g16 = (lane >> 4) & 1;
;   const LAS unsigned char* va = Vt + (4 * h + (i16 >> 2)) * VSTR + (16 * g16 + 4 * (i16 & 3)) * 2;
;   bf16x8 vc[NDV];
; #pragma unroll
;   for (int d = 0; d < NDV; ++d) { const v4i16_t lo = vtr(va + d * 64), hi = vtr(va + 8 * VSTR + d * 64); vc[d] = __builtin_shufflevector(lo, hi, 0, 1, 2, 3, 4, 5, 6, 7); }
; #pragma unroll
;   for (int ks = 0; ks < 4; ++ks) {
;     bf16x8 vn[NDV];
; #pragma unroll
;     for (int d = 0; d < NDV; ++d) { vn[d] = vc[d];
;       if (ks + 1 < 4) { const v4i16_t lo = vtr(va + (16 * (ks + 1)) * VSTR + d * 64), hi = vtr(va + (16 * (ks + 1) + 8) * VSTR + d * 64); vn[d] = __builtin_shufflevector(lo, hi, 0, 1, 2, 3, 4, 5, 6, 7); } }
; #pragma unroll
;     for (int d = 0; d < NDV; ++d) o[d] = mfma32(vc[d], pf[ks], o[d]);
;     if (ks + 1 < 4) __builtin_amdgcn_sched_group_barrier(0x100, 2 * NDV, 0);
;     __builtin_amdgcn_sched_group_barrier(0x008, NDV, 0);
; #pragma unroll
;     for (int d = 0; d < NDV; ++d) vc[d] = vn[d];
;   }
	v_exp_f32_e32 v39, v39
	v_add_f32_e32 v157, v157, v36
	v_add_f32_e32 v158, v158, v37
	v_cvt_pk_bf16_f32 v33, v34, v35
	v_sub_f32_e32 v40, v40, v152
	v_sub_f32_e32 v41, v41, v152
	v_exp_f32_e32 v40, v40
	v_exp_f32_e32 v41, v41
	v_add_f32_e32 v157, v157, v38
	v_add_f32_e32 v158, v158, v39
	v_cvt_pk_bf16_f32 v34, v36, v37
	v_sub_f32_e32 v42, v42, v152
	v_sub_f32_e32 v43, v43, v152
	v_exp_f32_e32 v42, v42
	v_exp_f32_e32 v43, v43
	v_add_f32_e32 v157, v157, v40
	v_add_f32_e32 v158, v158, v41
	v_cvt_pk_bf16_f32 v35, v38, v39
	v_sub_f32_e32 v44, v44, v152
	v_sub_f32_e32 v45, v45, v152
	v_exp_f32_e32 v44, v44
	v_exp_f32_e32 v45, v45
	v_add_f32_e32 v157, v157, v42
	v_add_f32_e32 v158, v158, v43
	v_cvt_pk_bf16_f32 v36, v40, v41
	v_sub_f32_e32 v46, v46, v152
	v_sub_f32_e32 v47, v47, v152
	v_exp_f32_e32 v46, v46
	v_exp_f32_e32 v47, v47
	v_add_f32_e32 v157, v157, v44
	v_add_f32_e32 v158, v158, v45
	v_cvt_pk_bf16_f32 v37, v42, v43
	s_nop 0
	v_add_f32_e32 v157, v157, v46
	v_add_f32_e32 v158, v158, v47
	v_cvt_pk_bf16_f32 v38, v44, v45
	v_cvt_pk_bf16_f32 v39, v46, v47
	v_sub_f32_e32 v48, v48, v152
	v_sub_f32_e32 v49, v49, v152
	v_exp_f32_e32 v48, v48
	v_exp_f32_e32 v49, v49
	v_sub_f32_e32 v50, v50, v152
	v_sub_f32_e32 v51, v51, v152
	v_exp_f32_e32 v50, v50
	v_exp_f32_e32 v51, v51
	v_add_f32_e32 v157, v157, v48
	v_add_f32_e32 v158, v158, v49
	v_sub_f32_e32 v52, v52, v152
	v_sub_f32_e32 v53, v53, v152
	v_exp_f32_e32 v52, v52
	v_exp_f32_e32 v53, v53
	v_add_f32_e32 v157, v157, v50
	v_add_f32_e32 v158, v158, v51
	v_cvt_pk_bf16_f32 v48, v48, v49
	v_sub_f32_e32 v54, v54, v152
	v_sub_f32_e32 v55, v55, v152
	v_exp_f32_e32 v54, v54
	v_exp_f32_e32 v55, v55
	v_add_f32_e32 v157, v157, v52
	v_add_f32_e32 v158, v158, v53
	v_cvt_pk_bf16_f32 v49, v50, v51
	v_sub_f32_e32 v56, v56, v152
	v_sub_f32_e32 v57, v57, v152
	v_exp_f32_e32 v56, v56
	v_exp_f32_e32 v57, v57
	v_add_f32_e32 v157, v157, v54
	v_add_f32_e32 v158, v158, v55
	v_cvt_pk_bf16_f32 v50, v52, v53
	v_sub_f32_e32 v58, v58, v152
	v_sub_f32_e32 v59, v59, v152
	v_exp_f32_e32 v58, v58
	v_exp_f32_e32 v59, v59
	v_add_f32_e32 v157, v157, v56
	v_add_f32_e32 v158, v158, v57
	v_cvt_pk_bf16_f32 v51, v54, v55
	v_sub_f32_e32 v60, v60, v152
	v_sub_f32_e32 v61, v61, v152
	v_exp_f32_e32 v60, v60
	v_exp_f32_e32 v61, v61
	v_add_f32_e32 v157, v157, v58
	v_add_f32_e32 v158, v158, v59
	v_cvt_pk_bf16_f32 v52, v56, v57
	v_sub_f32_e32 v62, v62, v152
	v_sub_f32_e32 v63, v63, v152
	v_exp_f32_e32 v62, v62
	v_exp_f32_e32 v63, v63
	v_add_f32_e32 v157, v157, v60
	v_add_f32_e32 v158, v158, v61
	v_cvt_pk_bf16_f32 v53, v58, v59
	s_nop 0
	v_add_f32_e32 v157, v157, v62
	v_add_f32_e32 v158, v158, v63
	v_cvt_pk_bf16_f32 v54, v60, v61
	v_cvt_pk_bf16_f32 v55, v62, v63
	v_sub_f32_e32 v64, v64, v152
	v_sub_f32_e32 v65, v65, v152
	v_exp_f32_e32 v64, v64
	v_exp_f32_e32 v65, v65
	v_sub_f32_e32 v66, v66, v152
	v_sub_f32_e32 v67, v67, v152
	v_exp_f32_e32 v66, v66
	v_exp_f32_e32 v67, v67
	v_add_f32_e32 v157, v157, v64
	v_add_f32_e32 v158, v158, v65
	v_sub_f32_e32 v68, v68, v152
	v_sub_f32_e32 v69, v69, v152
	v_exp_f32_e32 v68, v68
	v_exp_f32_e32 v69, v69
	v_add_f32_e32 v157, v157, v66
	v_add_f32_e32 v158, v158, v67
	v_cvt_pk_bf16_f32 v64, v64, v65
	v_sub_f32_e32 v70, v70, v152
	v_sub_f32_e32 v71, v71, v152
	v_exp_f32_e32 v70, v70
	v_exp_f32_e32 v71, v71
	v_add_f32_e32 v157, v157, v68
	v_add_f32_e32 v158, v158, v69
	v_cvt_pk_bf16_f32 v65, v66, v67
	v_sub_f32_e32 v72, v72, v152
	v_sub_f32_e32 v73, v73, v152
	v_exp_f32_e32 v72, v72
	v_exp_f32_e32 v73, v73
	v_add_f32_e32 v157, v157, v70
	v_add_f32_e32 v158, v158, v71
	v_cvt_pk_bf16_f32 v66, v68, v69
	v_sub_f32_e32 v74, v74, v152
	v_sub_f32_e32 v75, v75, v152
	v_exp_f32_e32 v74, v74
	v_exp_f32_e32 v75, v75
	v_add_f32_e32 v157, v157, v72
	v_add_f32_e32 v158, v158, v73
	v_cvt_pk_bf16_f32 v67, v70, v71
	v_sub_f32_e32 v76, v76, v152
	v_sub_f32_e32 v77, v77, v152
	v_exp_f32_e32 v76, v76
	v_exp_f32_e32 v77, v77
	v_add_f32_e32 v157, v157, v74
	v_add_f32_e32 v158, v158, v75
	v_cvt_pk_bf16_f32 v68, v72, v73
	v_sub_f32_e32 v78, v78, v152
	v_sub_f32_e32 v79, v79, v152
	v_exp_f32_e32 v78, v78
	v_exp_f32_e32 v79, v79
	v_add_f32_e32 v157, v157, v76
	v_add_f32_e32 v158, v158, v77
	v_cvt_pk_bf16_f32 v69, v74, v75
	s_nop 0
	v_add_f32_e32 v157, v157, v78
	v_add_f32_e32 v158, v158, v79
	v_cvt_pk_bf16_f32 v70, v76, v77
	v_cvt_pk_bf16_f32 v71, v78, v79
	v_add_f32_e32 v157, v157, v158
	ds_read_b64_tr_b16 v[208:209], v147 offset:18432
	ds_read_b64_tr_b16 v[210:211], v147 offset:19968
	s_waitcnt lgkmcnt(8)
	v_mfma_f32_32x32x16_bf16 v[160:175], v[192:195], v[0:3], 0
	ds_read_b64_tr_b16 v[212:213], v147 offset:18496
	ds_read_b64_tr_b16 v[214:215], v147 offset:20032
	s_waitcnt lgkmcnt(8)
	v_mfma_f32_32x32x16_bf16 v[176:191], v[196:199], v[0:3], 0
	ds_read_b64_tr_b16 v[216:217], v147 offset:21504
	ds_read_b64_tr_b16 v[218:219], v147 offset:23040
	s_waitcnt lgkmcnt(8)
	v_mfma_f32_32x32x16_bf16 v[160:175], v[200:203], v[4:7], v[160:175]
	ds_read_b64_tr_b16 v[220:221], v147 offset:21568
	ds_read_b64_tr_b16 v[222:223], v147 offset:23104
	s_waitcnt lgkmcnt(8)
	v_mfma_f32_32x32x16_bf16 v[176:191], v[204:207], v[4:7], v[176:191]
	ds_read_b64_tr_b16 v[192:193], v147 offset:36864
	ds_read_b64_tr_b16 v[194:195], v147 offset:38400
	s_waitcnt lgkmcnt(8)
	v_mfma_f32_32x32x16_bf16 v[160:175], v[208:211], v[16:19], v[160:175]
	ds_read_b64_tr_b16 v[196:197], v147 offset:36928
	ds_read_b64_tr_b16 v[198:199], v147 offset:38464
	s_waitcnt lgkmcnt(8)
	v_mfma_f32_32x32x16_bf16 v[176:191], v[212:215], v[16:19], v[176:191]
	ds_read_b64_tr_b16 v[200:201], v147 offset:39936
	ds_read_b64_tr_b16 v[202:203], v147 offset:41472
	s_waitcnt lgkmcnt(8)
; __device__ __forceinline__ float fexp2(float x) { return __builtin_amdgcn_exp2f(x); }
; __device__ __forceinline__ float frcp(float x) { return __builtin_amdgcn_rcpf(x); }
; __device__ __forceinline__ f32x16 mfma32(bf16x8 a, bf16x8 b, f32x16 c) { return __builtin_amdgcn_mfma_f32_32x32x16_bf16(a, b, c, 0, 0, 0); }
; __device__ __forceinline__ v4i16_t vtr(const LAS unsigned char* p) { return __builtin_amdgcn_ds_read_tr16_b64_v4i16((LAS v4i16_t*)p); }
; template <int NQK, int NDV, int KSTR, int VSTR> ...
;     ...
;   for (int ks = 0; ks < 4; ++ks) {
;     bf16x8 vn[NDV];
; #pragma unroll
;     for (int d = 0; d < NDV; ++d) { vn[d] = vc[d];
;       if (ks + 1 < 4) { const v4i16_t lo = vtr(va + (16 * (ks + 1)) * VSTR + d * 64), hi = vtr(va + (16 * (ks + 1) + 8) * VSTR + d * 64); vn[d] = __builtin_shufflevector(lo, hi, 0, 1, 2, 3, 4, 5, 6, 7); } }
; #pragma unroll
;     for (int d = 0; d < NDV; ++d) o[d] = mfma32(vc[d], pf[ks], o[d]);
;     if (ks + 1 < 4) __builtin_amdgcn_sched_group_barrier(0x100, 2 * NDV, 0);
;     __builtin_amdgcn_sched_group_barrier(0x008, NDV, 0);
; #pragma unroll
;     for (int d = 0; d < NDV; ++d) vc[d] = vn[d];
;   }
;     ...
;       const float inv = frcp(ls + __shfl_xor(ls, 32) + fexp2(sink2 - m));
;       bf16_t* qrow = qrow0 + (size_t)sub * 32 * LDH;
; #pragma unroll
;       for (int d = 0; d < 2; ++d)
; #pragma unroll
;         for (int g = 0; g < 4; ++g) { u32x2 w; w.x = pk2(o[d][4 * g] * inv, o[d][4 * g + 1] * inv); w.y = pk2(o[d][4 * g + 2] * inv, o[d][4 * g + 3] * inv);
;           bf16_t* dst_ = dummy ? (bf16_t*)(p->ws + O_Q) + (tokb + t0 + 32 * sub + c) * 1024 + hq * 64 : qrow; *(u32x2*)(dst_ + 32 * d + 8 * g + 4 * hh) = w; }
	v_mfma_f32_32x32x16_bf16 v[160:175], v[216:219], v[20:23], v[160:175]
	ds_read_b64_tr_b16 v[204:205], v147 offset:40000
	ds_read_b64_tr_b16 v[206:207], v147 offset:41536
	s_waitcnt lgkmcnt(8)
	v_mfma_f32_32x32x16_bf16 v[176:191], v[220:223], v[20:23], v[176:191]
	ds_read_b64_tr_b16 v[208:209], v147 offset:43008
	ds_read_b64_tr_b16 v[210:211], v147 offset:44544
	s_waitcnt lgkmcnt(8)
	v_mfma_f32_32x32x16_bf16 v[160:175], v[192:195], v[32:35], v[160:175]
	ds_read_b64_tr_b16 v[212:213], v147 offset:43072
	ds_read_b64_tr_b16 v[214:215], v147 offset:44608
	s_waitcnt lgkmcnt(8)
	v_mfma_f32_32x32x16_bf16 v[176:191], v[196:199], v[32:35], v[176:191]
	ds_read_b64_tr_b16 v[216:217], v147 offset:46080
	ds_read_b64_tr_b16 v[218:219], v147 offset:47616
	s_waitcnt lgkmcnt(8)
	v_mfma_f32_32x32x16_bf16 v[160:175], v[200:203], v[36:39], v[160:175]
	ds_read_b64_tr_b16 v[220:221], v147 offset:46144
	ds_read_b64_tr_b16 v[222:223], v147 offset:47680
	s_waitcnt lgkmcnt(8)
	v_mfma_f32_32x32x16_bf16 v[176:191], v[204:207], v[36:39], v[176:191]
	ds_read_b64_tr_b16 v[192:193], v148 offset:0
	ds_read_b64_tr_b16 v[194:195], v148 offset:1536
	s_waitcnt lgkmcnt(8)
	v_mfma_f32_32x32x16_bf16 v[160:175], v[208:211], v[48:51], v[160:175]
	ds_read_b64_tr_b16 v[196:197], v148 offset:64
	ds_read_b64_tr_b16 v[198:199], v148 offset:1600
	s_waitcnt lgkmcnt(8)
	v_mfma_f32_32x32x16_bf16 v[176:191], v[212:215], v[48:51], v[176:191]
	ds_read_b64_tr_b16 v[200:201], v148 offset:3072
	ds_read_b64_tr_b16 v[202:203], v148 offset:4608
	s_waitcnt lgkmcnt(8)
	v_mfma_f32_32x32x16_bf16 v[160:175], v[216:219], v[52:55], v[160:175]
	ds_read_b64_tr_b16 v[204:205], v148 offset:3136
	ds_read_b64_tr_b16 v[206:207], v148 offset:4672
	s_waitcnt lgkmcnt(8)
	v_mfma_f32_32x32x16_bf16 v[176:191], v[220:223], v[52:55], v[176:191]
	s_waitcnt lgkmcnt(6)
	v_mfma_f32_32x32x16_bf16 v[160:175], v[192:195], v[64:67], v[160:175]
	s_waitcnt lgkmcnt(4)
	v_mfma_f32_32x32x16_bf16 v[176:191], v[196:199], v[64:67], v[176:191]
	s_waitcnt lgkmcnt(2)
	v_mfma_f32_32x32x16_bf16 v[160:175], v[200:203], v[68:71], v[160:175]
	s_waitcnt lgkmcnt(0)
	v_mfma_f32_32x32x16_bf16 v[176:191], v[204:207], v[68:71], v[176:191]
	v_mov_b32_e32 v153, v157
	v_sub_f32_e32 v154, v135, v152
	v_exp_f32_e32 v154, v154
	v_permlane32_swap_b32_e32 v157, v153
	s_nop 0
	v_add_f32_e32 v157, v157, v153
	v_add_f32_e32 v157, v157, v154
	v_rcp_f32_e32 v159, v157
	v_lshrrev_b32_e32 v226, 1, v96
	v_mov_b32_e32 v227, 0
	v_lshl_add_u64 v[224:225], v[136:137], 0, v[226:227]
	s_nop 7
	v_mul_f32_e32 v160, v160, v159
	v_mul_f32_e32 v161, v161, v159
	v_mul_f32_e32 v162, v162, v159
	v_mul_f32_e32 v163, v163, v159
	v_cvt_pk_bf16_f32 v160, v160, v161
	v_cvt_pk_bf16_f32 v161, v162, v163
	global_store_dwordx2 v[224:225], v[160:161], off offset:0
	v_mul_f32_e32 v164, v164, v159
	v_mul_f32_e32 v165, v165, v159
	v_mul_f32_e32 v166, v166, v159
	v_mul_f32_e32 v167, v167, v159
	v_cvt_pk_bf16_f32 v164, v164, v165
	v_cvt_pk_bf16_f32 v165, v166, v167
	global_store_dwordx2 v[224:225], v[164:165], off offset:16
	v_mul_f32_e32 v168, v168, v159
	v_mul_f32_e32 v169, v169, v159
	v_mul_f32_e32 v170, v170, v159
	v_mul_f32_e32 v171, v171, v159
	v_cvt_pk_bf16_f32 v168, v168, v169
	v_cvt_pk_bf16_f32 v169, v170, v171
	global_store_dwordx2 v[224:225], v[168:169], off offset:32
	v_mul_f32_e32 v172, v172, v159
	v_mul_f32_e32 v173, v173, v159
	v_mul_f32_e32 v174, v174, v159
	v_mul_f32_e32 v175, v175, v159
	v_cvt_pk_bf16_f32 v172, v172, v173
	v_cvt_pk_bf16_f32 v173, v174, v175
	global_store_dwordx2 v[224:225], v[172:173], off offset:48
	v_mul_f32_e32 v176, v176, v159
	v_mul_f32_e32 v177, v177, v159
	v_mul_f32_e32 v178, v178, v159
	v_mul_f32_e32 v179, v179, v159
	v_cvt_pk_bf16_f32 v176, v176, v177
	v_cvt_pk_bf16_f32 v177, v178, v179
	global_store_dwordx2 v[224:225], v[176:177], off offset:64
	v_mul_f32_e32 v180, v180, v159
	v_mul_f32_e32 v181, v181, v159
	v_mul_f32_e32 v182, v182, v159
	v_mul_f32_e32 v183, v183, v159
	v_cvt_pk_bf16_f32 v180, v180, v181
	v_cvt_pk_bf16_f32 v181, v182, v183
	global_store_dwordx2 v[224:225], v[180:181], off offset:80
	v_mul_f32_e32 v184, v184, v159
	v_mul_f32_e32 v185, v185, v159
	v_mul_f32_e32 v186, v186, v159
	v_mul_f32_e32 v187, v187, v159
	v_cvt_pk_bf16_f32 v184, v184, v185
	v_cvt_pk_bf16_f32 v185, v186, v187
	global_store_dwordx2 v[224:225], v[184:185], off offset:96
	v_mul_f32_e32 v188, v188, v159
	v_mul_f32_e32 v189, v189, v159
	v_mul_f32_e32 v190, v190, v159
	v_mul_f32_e32 v191, v191, v159
	v_cvt_pk_bf16_f32 v188, v188, v189
	v_cvt_pk_bf16_f32 v189, v190, v191
	global_store_dwordx2 v[224:225], v[188:189], off offset:112
	ds_read_b128 v[80:83], v150 offset:4608
	ds_read_b128 v[84:87], v150 offset:4640
	ds_read_b128 v[88:91], v150 offset:4672
	ds_read_b128 v[92:95], v150 offset:4704
	s_waitcnt lgkmcnt(3)
	v_mfma_f32_32x32x16_bf16 v[0:15], v[80:83], v[110:113], 0
	ds_read_b128 v[80:83], v150 offset:24576
	s_waitcnt lgkmcnt(3)
	v_mfma_f32_32x32x16_bf16 v[0:15], v[84:87], v[106:109], v[0:15]
	ds_read_b128 v[84:87], v150 offset:24608
	s_waitcnt lgkmcnt(3)
	v_mfma_f32_32x32x16_bf16 v[0:15], v[88:91], v[102:105], v[0:15]
	ds_read_b128 v[88:91], v150 offset:24640
	s_waitcnt lgkmcnt(3)
	v_mfma_f32_32x32x16_bf16 v[0:15], v[92:95], v[98:101], v[0:15]
	ds_read_b128 v[92:95], v150 offset:24672
	s_waitcnt lgkmcnt(3)
	v_mfma_f32_32x32x16_bf16 v[16:31], v[80:83], v[110:113], 0
	ds_read_b128 v[80:83], v150 offset:29184
	s_waitcnt lgkmcnt(3)
	v_mfma_f32_32x32x16_bf16 v[16:31], v[84:87], v[106:109], v[16:31]
	ds_read_b128 v[84:87], v150 offset:29216
	s_waitcnt lgkmcnt(3)
	v_mfma_f32_32x32x16_bf16 v[16:31], v[88:91], v[102:105], v[16:31]
	ds_read_b128 v[88:91], v150 offset:29248
	s_waitcnt lgkmcnt(3)
; #define LAS __attribute__((address_space(3)))
; __device__ __forceinline__ f32x16 mfma32(bf16x8 a, bf16x8 b, f32x16 c) { return __builtin_amdgcn_mfma_f32_32x32x16_bf16(a, b, c, 0, 0, 0); }
; template <int NQK, int NDV, int KSTR, int VSTR> ...
;     ...
;   const LAS unsigned char* ka = Kt + c * KSTR + h * 16;
;   bf16x8 kc0 = *(const LAS bf16x8*)(ka), kc1 = *(const LAS bf16x8*)(ka + 32 * KSTR);
; #pragma unroll
;   for (int st = 0; st < NQK; ++st) {
;     bf16x8 kn0 = kc0, kn1 = kc1;
;     if (st + 1 < NQK) { kn0 = *(const LAS bf16x8*)(ka + (st + 1) * 32); kn1 = *(const LAS bf16x8*)(ka + 32 * KSTR + (st + 1) * 32); }
;     s0 = mfma32(kc0, qf[st], s0);
;     s1 = mfma32(kc1, qf[st], s1);
;     if (st + 1 < NQK) __builtin_amdgcn_sched_group_barrier(0x100, 2, 0);
;     __builtin_amdgcn_sched_group_barrier(0x008, 2, 0);
;     kc0 = kn0; kc1 = kn1;
;   }
;   if (domask) {
; #pragma unroll
;     for (int r = 0; r < 16; ++r) { const int kp = kpos0 + (r & 3) + 8 * (r >> 2) + 4 * h;
;       const bool v0 = (kp <= qpos) && (kp > qpos - window) && (kp >= 0);
;       const bool v1 = (kp + 32 <= qpos) && (kp + 32 > qpos - window) && (kp + 32 >= 0);
;       s0[r] = v0 ? s0[r] : -1e30f; s1[r] = v1 ? s1[r] : -1e30f; }
;   }
	v_mfma_f32_32x32x16_bf16 v[16:31], v[92:95], v[98:101], v[16:31]
	ds_read_b128 v[92:95], v150 offset:29280
	s_waitcnt lgkmcnt(3)
	v_mfma_f32_32x32x16_bf16 v[32:47], v[80:83], v[110:113], 0
	ds_read_b128 v[80:83], v150 offset:49152
	s_waitcnt lgkmcnt(3)
	v_mfma_f32_32x32x16_bf16 v[32:47], v[84:87], v[106:109], v[32:47]
	ds_read_b128 v[84:87], v150 offset:49184
	s_waitcnt lgkmcnt(3)
	v_mfma_f32_32x32x16_bf16 v[32:47], v[88:91], v[102:105], v[32:47]
	ds_read_b128 v[88:91], v150 offset:49216
	s_waitcnt lgkmcnt(3)
	v_mfma_f32_32x32x16_bf16 v[32:47], v[92:95], v[98:101], v[32:47]
	ds_read_b128 v[92:95], v150 offset:49248
	s_waitcnt lgkmcnt(3)
	v_mfma_f32_32x32x16_bf16 v[48:63], v[80:83], v[110:113], 0
	ds_read_b128 v[80:83], v150 offset:53760
	s_waitcnt lgkmcnt(3)
	v_mfma_f32_32x32x16_bf16 v[48:63], v[84:87], v[106:109], v[48:63]
	ds_read_b128 v[84:87], v150 offset:53792
	s_waitcnt lgkmcnt(3)
	v_mfma_f32_32x32x16_bf16 v[48:63], v[88:91], v[102:105], v[48:63]
	ds_read_b128 v[88:91], v150 offset:53824
	s_waitcnt lgkmcnt(3)
	v_mfma_f32_32x32x16_bf16 v[48:63], v[92:95], v[98:101], v[48:63]
	ds_read_b128 v[92:95], v150 offset:53856
	s_waitcnt lgkmcnt(3)
	v_mfma_f32_32x32x16_bf16 v[64:79], v[80:83], v[110:113], 0
	s_waitcnt lgkmcnt(2)
	v_mfma_f32_32x32x16_bf16 v[64:79], v[84:87], v[106:109], v[64:79]
	s_waitcnt lgkmcnt(1)
	v_mfma_f32_32x32x16_bf16 v[64:79], v[88:91], v[102:105], v[64:79]
	s_waitcnt lgkmcnt(0)
	v_mfma_f32_32x32x16_bf16 v[64:79], v[92:95], v[98:101], v[64:79]
	v_sub_u32_e32 v156, v133, v132
	v_mov_b32_e32 v155, 0xf149f2ca
	s_nop 4
	s_nop 4
	v_cmp_gt_i32_e64 s[26:27], 0, v156
	v_cmp_gt_i32_e64 s[28:29], 1, v156
	v_cmp_gt_i32_e64 s[30:31], 2, v156
	v_cmp_gt_i32_e64 s[34:35], 3, v156
	v_cndmask_b32_e64 v0, v155, v0, s[26:27]
	v_cndmask_b32_e64 v1, v155, v1, s[28:29]
	v_cndmask_b32_e64 v2, v155, v2, s[30:31]
	v_cndmask_b32_e64 v3, v155, v3, s[34:35]
	v_cmp_gt_i32_e64 s[26:27], 8, v156
	v_cmp_gt_i32_e64 s[28:29], 9, v156
	v_cmp_gt_i32_e64 s[30:31], 10, v156
	v_cmp_gt_i32_e64 s[34:35], 11, v156
	v_cndmask_b32_e64 v4, v155, v4, s[26:27]
	v_cndmask_b32_e64 v5, v155, v5, s[28:29]
	v_cndmask_b32_e64 v6, v155, v6, s[30:31]
	v_cndmask_b32_e64 v7, v155, v7, s[34:35]
	v_cmp_gt_i32_e64 s[26:27], 16, v156
	v_cmp_gt_i32_e64 s[28:29], 17, v156
	v_cmp_gt_i32_e64 s[30:31], 18, v156
	v_cmp_gt_i32_e64 s[34:35], 19, v156
	v_cndmask_b32_e64 v8, v155, v8, s[26:27]
	v_cndmask_b32_e64 v9, v155, v9, s[28:29]
	v_cndmask_b32_e64 v10, v155, v10, s[30:31]
	v_cndmask_b32_e64 v11, v155, v11, s[34:35]
	v_cmp_gt_i32_e64 s[26:27], 24, v156
	v_cmp_gt_i32_e64 s[28:29], 25, v156
	v_cmp_gt_i32_e64 s[30:31], 26, v156
	v_cmp_gt_i32_e64 s[34:35], 27, v156
	v_cndmask_b32_e64 v12, v155, v12, s[26:27]
	v_cndmask_b32_e64 v13, v155, v13, s[28:29]
	v_cndmask_b32_e64 v14, v155, v14, s[30:31]
	v_cndmask_b32_e64 v15, v155, v15, s[34:35]
	v_cmp_le_i32_e64 s[26:27], 0, v156
	v_cmp_le_i32_e64 s[28:29], 1, v156
	v_cmp_le_i32_e64 s[30:31], 2, v156
	v_cmp_le_i32_e64 s[34:35], 3, v156
	v_cndmask_b32_e64 v64, v155, v64, s[26:27]
	v_cndmask_b32_e64 v65, v155, v65, s[28:29]
	v_cndmask_b32_e64 v66, v155, v66, s[30:31]
	v_cndmask_b32_e64 v67, v155, v67, s[34:35]
	v_cmp_le_i32_e64 s[26:27], 8, v156
	v_cmp_le_i32_e64 s[28:29], 9, v156
	v_cmp_le_i32_e64 s[30:31], 10, v156
	v_cmp_le_i32_e64 s[34:35], 11, v156
	v_cndmask_b32_e64 v68, v155, v68, s[26:27]
	v_cndmask_b32_e64 v69, v155, v69, s[28:29]
	v_cndmask_b32_e64 v70, v155, v70, s[30:31]
	v_cndmask_b32_e64 v71, v155, v71, s[34:35]
	v_cmp_le_i32_e64 s[26:27], 16, v156
	v_cmp_le_i32_e64 s[28:29], 17, v156
	v_cmp_le_i32_e64 s[30:31], 18, v156
	v_cmp_le_i32_e64 s[34:35], 19, v156
	v_cndmask_b32_e64 v72, v155, v72, s[26:27]
	v_cndmask_b32_e64 v73, v155, v73, s[28:29]
	v_cndmask_b32_e64 v74, v155, v74, s[30:31]
	v_cndmask_b32_e64 v75, v155, v75, s[34:35]
	v_cmp_le_i32_e64 s[26:27], 24, v156
	v_cmp_le_i32_e64 s[28:29], 25, v156
	v_cmp_le_i32_e64 s[30:31], 26, v156
	v_cmp_le_i32_e64 s[34:35], 27, v156
	v_cndmask_b32_e64 v76, v155, v76, s[26:27]
	v_cndmask_b32_e64 v77, v155, v77, s[28:29]
	v_cndmask_b32_e64 v78, v155, v78, s[30:31]
	v_cndmask_b32_e64 v79, v155, v79, s[34:35]
	s_add_u32 s36, s23, 32
	s_cmp_ge_u32 s36, 128
	s_cbranch_scc1 .Lsw1_ok0
	v_mov_b32_e32 v0, v155
	v_mov_b32_e32 v1, v155
	v_mov_b32_e32 v2, v155
	v_mov_b32_e32 v3, v155
	v_mov_b32_e32 v4, v155
	v_mov_b32_e32 v5, v155
	v_mov_b32_e32 v6, v155
	v_mov_b32_e32 v7, v155
	v_mov_b32_e32 v8, v155
	v_mov_b32_e32 v9, v155
	v_mov_b32_e32 v10, v155
	v_mov_b32_e32 v11, v155
	v_mov_b32_e32 v12, v155
	v_mov_b32_e32 v13, v155
	v_mov_b32_e32 v14, v155
	v_mov_b32_e32 v15, v155
.Lsw1_ok0:
	s_add_u32 s36, s23, 64
	s_cmp_ge_u32 s36, 128
	s_cbranch_scc1 .Lsw1_ok1
	v_mov_b32_e32 v16, v155
	v_mov_b32_e32 v17, v155
	v_mov_b32_e32 v18, v155
	v_mov_b32_e32 v19, v155
	v_mov_b32_e32 v20, v155
	v_mov_b32_e32 v21, v155
	v_mov_b32_e32 v22, v155
	v_mov_b32_e32 v23, v155
	v_mov_b32_e32 v24, v155
	v_mov_b32_e32 v25, v155
	v_mov_b32_e32 v26, v155
	v_mov_b32_e32 v27, v155
	v_mov_b32_e32 v28, v155
	v_mov_b32_e32 v29, v155
	v_mov_b32_e32 v30, v155
	v_mov_b32_e32 v31, v155
.Lsw1_ok1:
	s_add_u32 s36, s23, 96
	s_cmp_ge_u32 s36, 128
	s_cbranch_scc1 .Lsw1_ok2
	v_mov_b32_e32 v32, v155
	v_mov_b32_e32 v33, v155
	v_mov_b32_e32 v34, v155
	v_mov_b32_e32 v35, v155
	v_mov_b32_e32 v36, v155
	v_mov_b32_e32 v37, v155
	v_mov_b32_e32 v38, v155
	v_mov_b32_e32 v39, v155
	v_mov_b32_e32 v40, v155
	v_mov_b32_e32 v41, v155
	v_mov_b32_e32 v42, v155
	v_mov_b32_e32 v43, v155
	v_mov_b32_e32 v44, v155
	v_mov_b32_e32 v45, v155
	v_mov_b32_e32 v46, v155
	v_mov_b32_e32 v47, v155
; #define LAS __attribute__((address_space(3)))
; __device__ __forceinline__ float fexp2(float x) { return __builtin_amdgcn_exp2f(x); }
; __device__ __forceinline__ v4i16_t vtr(const LAS unsigned char* p) { return __builtin_amdgcn_ds_read_tr16_b64_v4i16((LAS v4i16_t*)p); }
; template <int NQK, int NDV, int KSTR, int VSTR> ...
;     ...
;   float mx = fmaxf(s0[0], s1[0]);
; #pragma unroll
;   for (int r = 1; r < 16; ++r) mx = fmaxf(mx, fmaxf(s0[r], s1[r]));
;   mx = fmaxf(mx, __shfl_xor(mx, 32));
;   if (__builtin_amdgcn_ballot_w64(mx > m + 8.0f) != 0ull) {
;     const float mn = fmaxf(m, mx), alpha = fexp2(m - mn);
;     m = mn; l *= alpha;
; #pragma unroll
;     for (int d = 0; d < NDV; ++d) o[d] *= alpha;
;   }
;   float ps = 0.f;
; #pragma unroll
;   for (int r = 0; r < 16; ++r) { s0[r] = fexp2(s0[r] - m); s1[r] = fexp2(s1[r] - m); ps += s0[r] + s1[r]; }
;   l += ps;
;   bf16x8 pf[4];
; #pragma unroll
;   for (int s = 0; s < 2; ++s) {
;     u32x4 w0, w1;
;     w0.x = pk2(s0[8 * s + 0], s0[8 * s + 1]); w0.y = pk2(s0[8 * s + 2], s0[8 * s + 3]); w0.z = pk2(s0[8 * s + 4], s0[8 * s + 5]); w0.w = pk2(s0[8 * s + 6], s0[8 * s + 7]);
;     w1.x = pk2(s1[8 * s + 0], s1[8 * s + 1]); w1.y = pk2(s1[8 * s + 2], s1[8 * s + 3]); w1.z = pk2(s1[8 * s + 4], s1[8 * s + 5]); w1.w = pk2(s1[8 * s + 6], s1[8 * s + 7]);
;     pf[s] = __builtin_bit_cast(bf16x8, w0); pf[2 + s] = __builtin_bit_cast(bf16x8, w1);
;   }
;   const int i16 = lane & 15, g16 = (lane >> 4) & 1;
;   const LAS unsigned char* va = Vt + (4 * h + (i16 >> 2)) * VSTR + (16 * g16 + 4 * (i16 & 3)) * 2;
;   bf16x8 vc[NDV];
; #pragma unroll
;   for (int d = 0; d < NDV; ++d) { const v4i16_t lo = vtr(va + d * 64), hi = vtr(va + 8 * VSTR + d * 64); vc[d] = __builtin_shufflevector(lo, hi, 0, 1, 2, 3, 4, 5, 6, 7); }
.Lsw1_ok2:
	s_add_u32 s36, s23, 128
	s_cmp_ge_u32 s36, 128
	s_cbranch_scc1 .Lsw1_ok3
	v_mov_b32_e32 v48, v155
	v_mov_b32_e32 v49, v155
	v_mov_b32_e32 v50, v155
	v_mov_b32_e32 v51, v155
	v_mov_b32_e32 v52, v155
	v_mov_b32_e32 v53, v155
	v_mov_b32_e32 v54, v155
	v_mov_b32_e32 v55, v155
	v_mov_b32_e32 v56, v155
	v_mov_b32_e32 v57, v155
	v_mov_b32_e32 v58, v155
	v_mov_b32_e32 v59, v155
	v_mov_b32_e32 v60, v155
	v_mov_b32_e32 v61, v155
	v_mov_b32_e32 v62, v155
	v_mov_b32_e32 v63, v155
.Lsw1_ok3:
	v_max3_f32 v152, v0, v1, v2
	v_max3_f32 v152, v152, v3, v4
	v_max3_f32 v152, v152, v5, v6
	v_max3_f32 v152, v152, v7, v8
	v_max3_f32 v152, v152, v9, v10
	v_max3_f32 v152, v152, v11, v12
	v_max3_f32 v152, v152, v13, v14
	v_max3_f32 v152, v152, v15, v16
	v_max3_f32 v152, v152, v17, v18
	v_max3_f32 v152, v152, v19, v20
	v_max3_f32 v152, v152, v21, v22
	v_max3_f32 v152, v152, v23, v24
	v_max3_f32 v152, v152, v25, v26
	v_max3_f32 v152, v152, v27, v28
	v_max3_f32 v152, v152, v29, v30
	v_max3_f32 v152, v152, v31, v32
	v_max3_f32 v152, v152, v33, v34
	v_max3_f32 v152, v152, v35, v36
	v_max3_f32 v152, v152, v37, v38
	v_max3_f32 v152, v152, v39, v40
	v_max3_f32 v152, v152, v41, v42
	v_max3_f32 v152, v152, v43, v44
	v_max3_f32 v152, v152, v45, v46
	v_max3_f32 v152, v152, v47, v48
	v_max3_f32 v152, v152, v49, v50
	v_max3_f32 v152, v152, v51, v52
	v_max3_f32 v152, v152, v53, v54
	v_max3_f32 v152, v152, v55, v56
	v_max3_f32 v152, v152, v57, v58
	v_max3_f32 v152, v152, v59, v60
	v_max3_f32 v152, v152, v61, v62
	v_max3_f32 v152, v152, v63, v64
	v_max3_f32 v152, v152, v65, v66
	v_max3_f32 v152, v152, v67, v68
	v_max3_f32 v152, v152, v69, v70
	v_max3_f32 v152, v152, v71, v72
	v_max3_f32 v152, v152, v73, v74
	v_max3_f32 v152, v152, v75, v76
	v_max3_f32 v152, v152, v77, v78
	v_max_f32_e32 v152, v152, v79
	v_mov_b32_e32 v153, v152
	s_nop 1
	v_permlane32_swap_b32_e32 v152, v153
	s_nop 0
	v_max3_f32 v152, v152, v153, v135
	ds_read_b64_tr_b16 v[192:193], v147 offset:18432
	ds_read_b64_tr_b16 v[194:195], v147 offset:19968
	ds_read_b64_tr_b16 v[196:197], v147 offset:18496
	ds_read_b64_tr_b16 v[198:199], v147 offset:20032
	ds_read_b64_tr_b16 v[200:201], v147 offset:21504
	ds_read_b64_tr_b16 v[202:203], v147 offset:23040
	ds_read_b64_tr_b16 v[204:205], v147 offset:21568
	ds_read_b64_tr_b16 v[206:207], v147 offset:23104
	v_mov_b32_e32 v157, 0
	v_mov_b32_e32 v158, 0
	v_sub_f32_e32 v0, v0, v152
	v_sub_f32_e32 v1, v1, v152
	v_exp_f32_e32 v0, v0
	v_exp_f32_e32 v1, v1
	v_sub_f32_e32 v2, v2, v152
	v_sub_f32_e32 v3, v3, v152
	v_exp_f32_e32 v2, v2
	v_exp_f32_e32 v3, v3
	v_add_f32_e32 v157, v157, v0
	v_add_f32_e32 v158, v158, v1
	v_sub_f32_e32 v4, v4, v152
	v_sub_f32_e32 v5, v5, v152
	v_exp_f32_e32 v4, v4
	v_exp_f32_e32 v5, v5
	v_add_f32_e32 v157, v157, v2
	v_add_f32_e32 v158, v158, v3
	v_cvt_pk_bf16_f32 v0, v0, v1
	v_sub_f32_e32 v6, v6, v152
	v_sub_f32_e32 v7, v7, v152
	v_exp_f32_e32 v6, v6
	v_exp_f32_e32 v7, v7
	v_add_f32_e32 v157, v157, v4
	v_add_f32_e32 v158, v158, v5
	v_cvt_pk_bf16_f32 v1, v2, v3
	v_sub_f32_e32 v8, v8, v152
	v_sub_f32_e32 v9, v9, v152
	v_exp_f32_e32 v8, v8
	v_exp_f32_e32 v9, v9
	v_add_f32_e32 v157, v157, v6
	v_add_f32_e32 v158, v158, v7
	v_cvt_pk_bf16_f32 v2, v4, v5
	v_sub_f32_e32 v10, v10, v152
	v_sub_f32_e32 v11, v11, v152
	v_exp_f32_e32 v10, v10
	v_exp_f32_e32 v11, v11
	v_add_f32_e32 v157, v157, v8
	v_add_f32_e32 v158, v158, v9
	v_cvt_pk_bf16_f32 v3, v6, v7
	v_sub_f32_e32 v12, v12, v152
	v_sub_f32_e32 v13, v13, v152
	v_exp_f32_e32 v12, v12
	v_exp_f32_e32 v13, v13
	v_add_f32_e32 v157, v157, v10
	v_add_f32_e32 v158, v158, v11
	v_cvt_pk_bf16_f32 v4, v8, v9
	v_sub_f32_e32 v14, v14, v152
	v_sub_f32_e32 v15, v15, v152
	v_exp_f32_e32 v14, v14
	v_exp_f32_e32 v15, v15
	v_add_f32_e32 v157, v157, v12
	v_add_f32_e32 v158, v158, v13
	v_cvt_pk_bf16_f32 v5, v10, v11
	s_nop 0
	v_add_f32_e32 v157, v157, v14
	v_add_f32_e32 v158, v158, v15
	v_cvt_pk_bf16_f32 v6, v12, v13
	v_cvt_pk_bf16_f32 v7, v14, v15
	v_sub_f32_e32 v16, v16, v152
	v_sub_f32_e32 v17, v17, v152
	v_exp_f32_e32 v16, v16
	v_exp_f32_e32 v17, v17
	v_sub_f32_e32 v18, v18, v152
	v_sub_f32_e32 v19, v19, v152
	v_exp_f32_e32 v18, v18
	v_exp_f32_e32 v19, v19
	v_add_f32_e32 v157, v157, v16
	v_add_f32_e32 v158, v158, v17
	v_sub_f32_e32 v20, v20, v152
	v_sub_f32_e32 v21, v21, v152
	v_exp_f32_e32 v20, v20
	v_exp_f32_e32 v21, v21
	v_add_f32_e32 v157, v157, v18
	v_add_f32_e32 v158, v158, v19
	v_cvt_pk_bf16_f32 v16, v16, v17
	v_sub_f32_e32 v22, v22, v152
	v_sub_f32_e32 v23, v23, v152
	v_exp_f32_e32 v22, v22
	v_exp_f32_e32 v23, v23
	v_add_f32_e32 v157, v157, v20
	v_add_f32_e32 v158, v158, v21
	v_cvt_pk_bf16_f32 v17, v18, v19
	v_sub_f32_e32 v24, v24, v152
	v_sub_f32_e32 v25, v25, v152
	v_exp_f32_e32 v24, v24
	v_exp_f32_e32 v25, v25
	v_add_f32_e32 v157, v157, v22
	v_add_f32_e32 v158, v158, v23
	v_cvt_pk_bf16_f32 v18, v20, v21
	v_sub_f32_e32 v26, v26, v152
	v_sub_f32_e32 v27, v27, v152
	v_exp_f32_e32 v26, v26
	v_exp_f32_e32 v27, v27
	v_add_f32_e32 v157, v157, v24
	v_add_f32_e32 v158, v158, v25
	v_cvt_pk_bf16_f32 v19, v22, v23
	v_sub_f32_e32 v28, v28, v152
	v_sub_f32_e32 v29, v29, v152
	v_exp_f32_e32 v28, v28
	v_exp_f32_e32 v29, v29
	v_add_f32_e32 v157, v157, v26
	v_add_f32_e32 v158, v158, v27
	v_cvt_pk_bf16_f32 v20, v24, v25
	v_sub_f32_e32 v30, v30, v152
	v_sub_f32_e32 v31, v31, v152
	v_exp_f32_e32 v30, v30
	v_exp_f32_e32 v31, v31
	v_add_f32_e32 v157, v157, v28
	v_add_f32_e32 v158, v158, v29
	v_cvt_pk_bf16_f32 v21, v26, v27
	s_nop 0
	v_add_f32_e32 v157, v157, v30
	v_add_f32_e32 v158, v158, v31
	v_cvt_pk_bf16_f32 v22, v28, v29
	v_cvt_pk_bf16_f32 v23, v30, v31
	v_sub_f32_e32 v32, v32, v152
	v_sub_f32_e32 v33, v33, v152
	v_exp_f32_e32 v32, v32
; #define LAS __attribute__((address_space(3)))
; __device__ __forceinline__ float fexp2(float x) { return __builtin_amdgcn_exp2f(x); }
; __device__ __forceinline__ f32x16 mfma32(bf16x8 a, bf16x8 b, f32x16 c) { return __builtin_amdgcn_mfma_f32_32x32x16_bf16(a, b, c, 0, 0, 0); }
; __device__ __forceinline__ v4i16_t vtr(const LAS unsigned char* p) { return __builtin_amdgcn_ds_read_tr16_b64_v4i16((LAS v4i16_t*)p); }
; template <int NQK, int NDV, int KSTR, int VSTR> ...
;     ...
;   float ps = 0.f;
; #pragma unroll
;   for (int r = 0; r < 16; ++r) { s0[r] = fexp2(s0[r] - m); s1[r] = fexp2(s1[r] - m); ps += s0[r] + s1[r]; }
;   l += ps;
;   bf16x8 pf[4];
; #pragma unroll
;   for (int s = 0; s < 2; ++s) {
;     u32x4 w0, w1;
;     w0.x = pk2(s0[8 * s + 0], s0[8 * s + 1]); w0.y = pk2(s0[8 * s + 2], s0[8 * s + 3]); w0.z = pk2(s0[8 * s + 4], s0[8 * s + 5]); w0.w = pk2(s0[8 * s + 6], s0[8 * s + 7]);
;     w1.x = pk2(s1[8 * s + 0], s1[8 * s + 1]); w1.y = pk2(s1[8 * s + 2], s1[8 * s + 3]); w1.z = pk2(s1[8 * s + 4], s1[8 * s + 5]); w1.w = pk2(s1[8 * s + 6], s1[8 * s + 7]);
;     pf[s] = __builtin_bit_cast(bf16x8, w0); pf[2 + s] = __builtin_bit_cast(bf16x8, w1);
;   }
;   const int i16 = lane & 15, g16 = (lane >> 4) & 1;
;   const LAS unsigned char* va = Vt + (4 * h + (i16 >> 2)) * VSTR + (16 * g16 + 4 * (i16 & 3)) * 2;
;   bf16x8 vc[NDV];
; #pragma unroll
;   for (int d = 0; d < NDV; ++d) { const v4i16_t lo = vtr(va + d * 64), hi = vtr(va + 8 * VSTR + d * 64); vc[d] = __builtin_shufflevector(lo, hi, 0, 1, 2, 3, 4, 5, 6, 7); }
; #pragma unroll
;   for (int ks = 0; ks < 4; ++ks) {
;     bf16x8 vn[NDV];
; #pragma unroll
;     for (int d = 0; d < NDV; ++d) { vn[d] = vc[d];
;       if (ks + 1 < 4) { const v4i16_t lo = vtr(va + (16 * (ks + 1)) * VSTR + d * 64), hi = vtr(va + (16 * (ks + 1) + 8) * VSTR + d * 64); vn[d] = __builtin_shufflevector(lo, hi, 0, 1, 2, 3, 4, 5, 6, 7); } }
; #pragma unroll
;     for (int d = 0; d < NDV; ++d) o[d] = mfma32(vc[d], pf[ks], o[d]);
;     if (ks + 1 < 4) __builtin_amdgcn_sched_group_barrier(0x100, 2 * NDV, 0);
;     __builtin_amdgcn_sched_group_barrier(0x008, NDV, 0);
; #pragma unroll
;     for (int d = 0; d < NDV; ++d) vc[d] = vn[d];
;   }
	v_exp_f32_e32 v33, v33
	v_sub_f32_e32 v34, v34, v152
	v_sub_f32_e32 v35, v35, v152
	v_exp_f32_e32 v34, v34
	v_exp_f32_e32 v35, v35
	v_add_f32_e32 v157, v157, v32
	v_add_f32_e32 v158, v158, v33
	v_sub_f32_e32 v36, v36, v152
	v_sub_f32_e32 v37, v37, v152
	v_exp_f32_e32 v36, v36
	v_exp_f32_e32 v37, v37
	v_add_f32_e32 v157, v157, v34
	v_add_f32_e32 v158, v158, v35
	v_cvt_pk_bf16_f32 v32, v32, v33
	v_sub_f32_e32 v38, v38, v152
	v_sub_f32_e32 v39, v39, v152
	v_exp_f32_e32 v38, v38
	v_exp_f32_e32 v39, v39
	v_add_f32_e32 v157, v157, v36
	v_add_f32_e32 v158, v158, v37
	v_cvt_pk_bf16_f32 v33, v34, v35
	v_sub_f32_e32 v40, v40, v152
	v_sub_f32_e32 v41, v41, v152
	v_exp_f32_e32 v40, v40
	v_exp_f32_e32 v41, v41
	v_add_f32_e32 v157, v157, v38
	v_add_f32_e32 v158, v158, v39
	v_cvt_pk_bf16_f32 v34, v36, v37
	v_sub_f32_e32 v42, v42, v152
	v_sub_f32_e32 v43, v43, v152
	v_exp_f32_e32 v42, v42
	v_exp_f32_e32 v43, v43
	v_add_f32_e32 v157, v157, v40
	v_add_f32_e32 v158, v158, v41
	v_cvt_pk_bf16_f32 v35, v38, v39
	v_sub_f32_e32 v44, v44, v152
	v_sub_f32_e32 v45, v45, v152
	v_exp_f32_e32 v44, v44
	v_exp_f32_e32 v45, v45
	v_add_f32_e32 v157, v157, v42
	v_add_f32_e32 v158, v158, v43
	v_cvt_pk_bf16_f32 v36, v40, v41
	v_sub_f32_e32 v46, v46, v152
	v_sub_f32_e32 v47, v47, v152
	v_exp_f32_e32 v46, v46
	v_exp_f32_e32 v47, v47
	v_add_f32_e32 v157, v157, v44
	v_add_f32_e32 v158, v158, v45
	v_cvt_pk_bf16_f32 v37, v42, v43
	s_nop 0
	v_add_f32_e32 v157, v157, v46
	v_add_f32_e32 v158, v158, v47
	v_cvt_pk_bf16_f32 v38, v44, v45
	v_cvt_pk_bf16_f32 v39, v46, v47
	v_sub_f32_e32 v48, v48, v152
	v_sub_f32_e32 v49, v49, v152
	v_exp_f32_e32 v48, v48
	v_exp_f32_e32 v49, v49
	v_sub_f32_e32 v50, v50, v152
	v_sub_f32_e32 v51, v51, v152
	v_exp_f32_e32 v50, v50
	v_exp_f32_e32 v51, v51
	v_add_f32_e32 v157, v157, v48
	v_add_f32_e32 v158, v158, v49
	v_sub_f32_e32 v52, v52, v152
	v_sub_f32_e32 v53, v53, v152
	v_exp_f32_e32 v52, v52
	v_exp_f32_e32 v53, v53
	v_add_f32_e32 v157, v157, v50
	v_add_f32_e32 v158, v158, v51
	v_cvt_pk_bf16_f32 v48, v48, v49
	v_sub_f32_e32 v54, v54, v152
	v_sub_f32_e32 v55, v55, v152
	v_exp_f32_e32 v54, v54
	v_exp_f32_e32 v55, v55
	v_add_f32_e32 v157, v157, v52
	v_add_f32_e32 v158, v158, v53
	v_cvt_pk_bf16_f32 v49, v50, v51
	v_sub_f32_e32 v56, v56, v152
	v_sub_f32_e32 v57, v57, v152
	v_exp_f32_e32 v56, v56
	v_exp_f32_e32 v57, v57
	v_add_f32_e32 v157, v157, v54
	v_add_f32_e32 v158, v158, v55
	v_cvt_pk_bf16_f32 v50, v52, v53
	v_sub_f32_e32 v58, v58, v152
	v_sub_f32_e32 v59, v59, v152
	v_exp_f32_e32 v58, v58
	v_exp_f32_e32 v59, v59
	v_add_f32_e32 v157, v157, v56
	v_add_f32_e32 v158, v158, v57
	v_cvt_pk_bf16_f32 v51, v54, v55
	v_sub_f32_e32 v60, v60, v152
	v_sub_f32_e32 v61, v61, v152
	v_exp_f32_e32 v60, v60
	v_exp_f32_e32 v61, v61
	v_add_f32_e32 v157, v157, v58
	v_add_f32_e32 v158, v158, v59
	v_cvt_pk_bf16_f32 v52, v56, v57
	v_sub_f32_e32 v62, v62, v152
	v_sub_f32_e32 v63, v63, v152
	v_exp_f32_e32 v62, v62
	v_exp_f32_e32 v63, v63
	v_add_f32_e32 v157, v157, v60
	v_add_f32_e32 v158, v158, v61
	v_cvt_pk_bf16_f32 v53, v58, v59
	s_nop 0
	v_add_f32_e32 v157, v157, v62
	v_add_f32_e32 v158, v158, v63
	v_cvt_pk_bf16_f32 v54, v60, v61
	v_cvt_pk_bf16_f32 v55, v62, v63
	v_sub_f32_e32 v64, v64, v152
	v_sub_f32_e32 v65, v65, v152
	v_exp_f32_e32 v64, v64
	v_exp_f32_e32 v65, v65
	v_sub_f32_e32 v66, v66, v152
	v_sub_f32_e32 v67, v67, v152
	v_exp_f32_e32 v66, v66
	v_exp_f32_e32 v67, v67
	v_add_f32_e32 v157, v157, v64
	v_add_f32_e32 v158, v158, v65
	v_sub_f32_e32 v68, v68, v152
	v_sub_f32_e32 v69, v69, v152
	v_exp_f32_e32 v68, v68
	v_exp_f32_e32 v69, v69
	v_add_f32_e32 v157, v157, v66
	v_add_f32_e32 v158, v158, v67
	v_cvt_pk_bf16_f32 v64, v64, v65
	v_sub_f32_e32 v70, v70, v152
	v_sub_f32_e32 v71, v71, v152
	v_exp_f32_e32 v70, v70
	v_exp_f32_e32 v71, v71
	v_add_f32_e32 v157, v157, v68
	v_add_f32_e32 v158, v158, v69
	v_cvt_pk_bf16_f32 v65, v66, v67
	v_sub_f32_e32 v72, v72, v152
	v_sub_f32_e32 v73, v73, v152
	v_exp_f32_e32 v72, v72
	v_exp_f32_e32 v73, v73
	v_add_f32_e32 v157, v157, v70
	v_add_f32_e32 v158, v158, v71
	v_cvt_pk_bf16_f32 v66, v68, v69
	v_sub_f32_e32 v74, v74, v152
	v_sub_f32_e32 v75, v75, v152
	v_exp_f32_e32 v74, v74
	v_exp_f32_e32 v75, v75
	v_add_f32_e32 v157, v157, v72
	v_add_f32_e32 v158, v158, v73
	v_cvt_pk_bf16_f32 v67, v70, v71
	v_sub_f32_e32 v76, v76, v152
	v_sub_f32_e32 v77, v77, v152
	v_exp_f32_e32 v76, v76
	v_exp_f32_e32 v77, v77
	v_add_f32_e32 v157, v157, v74
	v_add_f32_e32 v158, v158, v75
	v_cvt_pk_bf16_f32 v68, v72, v73
	v_sub_f32_e32 v78, v78, v152
	v_sub_f32_e32 v79, v79, v152
	v_exp_f32_e32 v78, v78
	v_exp_f32_e32 v79, v79
	v_add_f32_e32 v157, v157, v76
	v_add_f32_e32 v158, v158, v77
	v_cvt_pk_bf16_f32 v69, v74, v75
	s_nop 0
	v_add_f32_e32 v157, v157, v78
	v_add_f32_e32 v158, v158, v79
	v_cvt_pk_bf16_f32 v70, v76, v77
	v_cvt_pk_bf16_f32 v71, v78, v79
	v_add_f32_e32 v157, v157, v158
	ds_read_b64_tr_b16 v[208:209], v147 offset:36864
	ds_read_b64_tr_b16 v[210:211], v147 offset:38400
	s_waitcnt lgkmcnt(8)
	v_mfma_f32_32x32x16_bf16 v[160:175], v[192:195], v[0:3], 0
	ds_read_b64_tr_b16 v[212:213], v147 offset:36928
	ds_read_b64_tr_b16 v[214:215], v147 offset:38464
	s_waitcnt lgkmcnt(8)
	v_mfma_f32_32x32x16_bf16 v[176:191], v[196:199], v[0:3], 0
	ds_read_b64_tr_b16 v[216:217], v147 offset:39936
	ds_read_b64_tr_b16 v[218:219], v147 offset:41472
	s_waitcnt lgkmcnt(8)
; __device__ __forceinline__ float fexp2(float x) { return __builtin_amdgcn_exp2f(x); }
; __device__ __forceinline__ float frcp(float x) { return __builtin_amdgcn_rcpf(x); }
; __device__ __forceinline__ f32x16 mfma32(bf16x8 a, bf16x8 b, f32x16 c) { return __builtin_amdgcn_mfma_f32_32x32x16_bf16(a, b, c, 0, 0, 0); }
; __device__ __forceinline__ v4i16_t vtr(const LAS unsigned char* p) { return __builtin_amdgcn_ds_read_tr16_b64_v4i16((LAS v4i16_t*)p); }
; template <int NQK, int NDV, int KSTR, int VSTR> ...
;     ...
;   for (int ks = 0; ks < 4; ++ks) {
;     bf16x8 vn[NDV];
; #pragma unroll
;     for (int d = 0; d < NDV; ++d) { vn[d] = vc[d];
;       if (ks + 1 < 4) { const v4i16_t lo = vtr(va + (16 * (ks + 1)) * VSTR + d * 64), hi = vtr(va + (16 * (ks + 1) + 8) * VSTR + d * 64); vn[d] = __builtin_shufflevector(lo, hi, 0, 1, 2, 3, 4, 5, 6, 7); } }
; #pragma unroll
;     for (int d = 0; d < NDV; ++d) o[d] = mfma32(vc[d], pf[ks], o[d]);
;     if (ks + 1 < 4) __builtin_amdgcn_sched_group_barrier(0x100, 2 * NDV, 0);
;     __builtin_amdgcn_sched_group_barrier(0x008, NDV, 0);
; #pragma unroll
;     for (int d = 0; d < NDV; ++d) vc[d] = vn[d];
;   }
;     ...
;       const float inv = frcp(ls + __shfl_xor(ls, 32) + fexp2(sink2 - m));
;       bf16_t* qrow = qrow0 + (size_t)sub * 32 * LDH;
; #pragma unroll
;       for (int d = 0; d < 2; ++d)
; #pragma unroll
;         for (int g = 0; g < 4; ++g) { u32x2 w; w.x = pk2(o[d][4 * g] * inv, o[d][4 * g + 1] * inv); w.y = pk2(o[d][4 * g + 2] * inv, o[d][4 * g + 3] * inv);
;           bf16_t* dst_ = dummy ? (bf16_t*)(p->ws + O_Q) + (tokb + t0 + 32 * sub + c) * 1024 + hq * 64 : qrow; *(u32x2*)(dst_ + 32 * d + 8 * g + 4 * hh) = w; }
;     }
;     __syncthreads();
;   }
	v_mfma_f32_32x32x16_bf16 v[160:175], v[200:203], v[4:7], v[160:175]
	ds_read_b64_tr_b16 v[220:221], v147 offset:40000
	ds_read_b64_tr_b16 v[222:223], v147 offset:41536
	s_waitcnt lgkmcnt(8)
	v_mfma_f32_32x32x16_bf16 v[176:191], v[204:207], v[4:7], v[176:191]
	ds_read_b64_tr_b16 v[192:193], v147 offset:43008
	ds_read_b64_tr_b16 v[194:195], v147 offset:44544
	s_waitcnt lgkmcnt(8)
	v_mfma_f32_32x32x16_bf16 v[160:175], v[208:211], v[16:19], v[160:175]
	ds_read_b64_tr_b16 v[196:197], v147 offset:43072
	ds_read_b64_tr_b16 v[198:199], v147 offset:44608
	s_waitcnt lgkmcnt(8)
	v_mfma_f32_32x32x16_bf16 v[176:191], v[212:215], v[16:19], v[176:191]
	ds_read_b64_tr_b16 v[200:201], v147 offset:46080
	ds_read_b64_tr_b16 v[202:203], v147 offset:47616
	s_waitcnt lgkmcnt(8)
	v_mfma_f32_32x32x16_bf16 v[160:175], v[216:219], v[20:23], v[160:175]
	ds_read_b64_tr_b16 v[204:205], v147 offset:46144
	ds_read_b64_tr_b16 v[206:207], v147 offset:47680
	s_waitcnt lgkmcnt(8)
	v_mfma_f32_32x32x16_bf16 v[176:191], v[220:223], v[20:23], v[176:191]
	ds_read_b64_tr_b16 v[208:209], v148 offset:0
	ds_read_b64_tr_b16 v[210:211], v148 offset:1536
	s_waitcnt lgkmcnt(8)
	v_mfma_f32_32x32x16_bf16 v[160:175], v[192:195], v[32:35], v[160:175]
	ds_read_b64_tr_b16 v[212:213], v148 offset:64
	ds_read_b64_tr_b16 v[214:215], v148 offset:1600
	s_waitcnt lgkmcnt(8)
	v_mfma_f32_32x32x16_bf16 v[176:191], v[196:199], v[32:35], v[176:191]
	ds_read_b64_tr_b16 v[216:217], v148 offset:3072
	ds_read_b64_tr_b16 v[218:219], v148 offset:4608
	s_waitcnt lgkmcnt(8)
	v_mfma_f32_32x32x16_bf16 v[160:175], v[200:203], v[36:39], v[160:175]
	ds_read_b64_tr_b16 v[220:221], v148 offset:3136
	ds_read_b64_tr_b16 v[222:223], v148 offset:4672
	s_waitcnt lgkmcnt(8)
	v_mfma_f32_32x32x16_bf16 v[176:191], v[204:207], v[36:39], v[176:191]
	ds_read_b64_tr_b16 v[192:193], v148 offset:6144
	ds_read_b64_tr_b16 v[194:195], v148 offset:7680
	s_waitcnt lgkmcnt(8)
	v_mfma_f32_32x32x16_bf16 v[160:175], v[208:211], v[48:51], v[160:175]
	ds_read_b64_tr_b16 v[196:197], v148 offset:6208
	ds_read_b64_tr_b16 v[198:199], v148 offset:7744
	s_waitcnt lgkmcnt(8)
	v_mfma_f32_32x32x16_bf16 v[176:191], v[212:215], v[48:51], v[176:191]
	ds_read_b64_tr_b16 v[200:201], v148 offset:9216
	ds_read_b64_tr_b16 v[202:203], v148 offset:10752
	s_waitcnt lgkmcnt(8)
	v_mfma_f32_32x32x16_bf16 v[160:175], v[216:219], v[52:55], v[160:175]
	ds_read_b64_tr_b16 v[204:205], v148 offset:9280
	ds_read_b64_tr_b16 v[206:207], v148 offset:10816
	s_waitcnt lgkmcnt(8)
	v_mfma_f32_32x32x16_bf16 v[176:191], v[220:223], v[52:55], v[176:191]
	s_waitcnt lgkmcnt(6)
	v_mfma_f32_32x32x16_bf16 v[160:175], v[192:195], v[64:67], v[160:175]
	s_waitcnt lgkmcnt(4)
	v_mfma_f32_32x32x16_bf16 v[176:191], v[196:199], v[64:67], v[176:191]
	s_waitcnt lgkmcnt(2)
	v_mfma_f32_32x32x16_bf16 v[160:175], v[200:203], v[68:71], v[160:175]
	s_waitcnt lgkmcnt(0)
	v_mfma_f32_32x32x16_bf16 v[176:191], v[204:207], v[68:71], v[176:191]
	v_mov_b32_e32 v153, v157
	v_sub_f32_e32 v154, v135, v152
	v_exp_f32_e32 v154, v154
	v_permlane32_swap_b32_e32 v157, v153
	s_nop 0
	v_add_f32_e32 v157, v157, v153
	v_add_f32_e32 v157, v157, v154
	v_rcp_f32_e32 v159, v157
	v_lshrrev_b32_e32 v226, 1, v96
	v_mov_b32_e32 v227, 0
	v_lshl_add_u64 v[224:225], v[136:137], 0, v[226:227]
	v_lshl_add_u64 v[224:225], v[224:225], 0, s[68:69]
	s_nop 7
	v_mul_f32_e32 v160, v160, v159
	v_mul_f32_e32 v161, v161, v159
	v_mul_f32_e32 v162, v162, v159
	v_mul_f32_e32 v163, v163, v159
	v_cvt_pk_bf16_f32 v160, v160, v161
	v_cvt_pk_bf16_f32 v161, v162, v163
	global_store_dwordx2 v[224:225], v[160:161], off offset:0
	v_mul_f32_e32 v164, v164, v159
	v_mul_f32_e32 v165, v165, v159
	v_mul_f32_e32 v166, v166, v159
	v_mul_f32_e32 v167, v167, v159
	v_cvt_pk_bf16_f32 v164, v164, v165
	v_cvt_pk_bf16_f32 v165, v166, v167
	global_store_dwordx2 v[224:225], v[164:165], off offset:16
	v_mul_f32_e32 v168, v168, v159
	v_mul_f32_e32 v169, v169, v159
	v_mul_f32_e32 v170, v170, v159
	v_mul_f32_e32 v171, v171, v159
	v_cvt_pk_bf16_f32 v168, v168, v169
	v_cvt_pk_bf16_f32 v169, v170, v171
	global_store_dwordx2 v[224:225], v[168:169], off offset:32
	v_mul_f32_e32 v172, v172, v159
	v_mul_f32_e32 v173, v173, v159
	v_mul_f32_e32 v174, v174, v159
	v_mul_f32_e32 v175, v175, v159
	v_cvt_pk_bf16_f32 v172, v172, v173
	v_cvt_pk_bf16_f32 v173, v174, v175
	global_store_dwordx2 v[224:225], v[172:173], off offset:48
	v_mul_f32_e32 v176, v176, v159
	v_mul_f32_e32 v177, v177, v159
	v_mul_f32_e32 v178, v178, v159
	v_mul_f32_e32 v179, v179, v159
	v_cvt_pk_bf16_f32 v176, v176, v177
	v_cvt_pk_bf16_f32 v177, v178, v179
	global_store_dwordx2 v[224:225], v[176:177], off offset:64
	v_mul_f32_e32 v180, v180, v159
	v_mul_f32_e32 v181, v181, v159
	v_mul_f32_e32 v182, v182, v159
	v_mul_f32_e32 v183, v183, v159
	v_cvt_pk_bf16_f32 v180, v180, v181
	v_cvt_pk_bf16_f32 v181, v182, v183
	global_store_dwordx2 v[224:225], v[180:181], off offset:80
	v_mul_f32_e32 v184, v184, v159
	v_mul_f32_e32 v185, v185, v159
	v_mul_f32_e32 v186, v186, v159
	v_mul_f32_e32 v187, v187, v159
	v_cvt_pk_bf16_f32 v184, v184, v185
	v_cvt_pk_bf16_f32 v185, v186, v187
	global_store_dwordx2 v[224:225], v[184:185], off offset:96
	v_mul_f32_e32 v188, v188, v159
	v_mul_f32_e32 v189, v189, v159
	v_mul_f32_e32 v190, v190, v159
	v_mul_f32_e32 v191, v191, v159
	v_cvt_pk_bf16_f32 v188, v188, v189
	v_cvt_pk_bf16_f32 v189, v190, v191
	global_store_dwordx2 v[224:225], v[188:189], off offset:112
	s_add_i32 s16, s16, s17
	s_add_i32 s20, s20, s21
	s_barrier
	s_cmpk_lt_i32 s16, 0x200
	s_cbranch_scc1 .LBB0_585
